# GEMM K-loops: LDS-DMA loads use SGPR base + 32-bit offset form and are issued before the A-fragment ds_reads of their load segment
# speedup vs baseline: 1.0124x; 1.0124x over previous
.LBB0_94:
	ds_read_b128 v[142:145], v160
	ds_read_b128 v[146:149], v160 offset:1024
	ds_read_b128 v[168:171], v160 offset:2048
	ds_read_b128 v[172:175], v160 offset:3072
	ds_read_b128 v[176:179], v161
	ds_read_b128 v[180:183], v161 offset:1024
	ds_read_b128 v[184:187], v161 offset:2048
	ds_read_b128 v[188:191], v161 offset:3072
	s_add_u32 s24, s22, 0x4000
	s_addc_u32 s25, s23, 0
	s_cmp_eq_u32 s60, 60
	s_cselect_b32 s28, s2, s24
	s_cselect_b32 s29, s1, s25
	s_cselect_b32 s26, s15, s48
	s_cselect_b32 s27, s13, s49
	s_add_u32 s24, s28, 0x8000
	s_addc_u32 s25, s29, 0
	s_add_i32 m0, s21, 0xc000
	s_nop 0
	global_load_lds_dwordx4 v128, s[22:23]
	s_add_i32 m0, s21, 0xe000
	s_nop 0
	global_load_lds_dwordx4 v130, s[22:23]
	ds_read_b128 v[196:199], v162
	ds_read_b128 v[200:203], v162 offset:1024
	ds_read_b128 v[204:207], v162 offset:2048
	ds_read_b128 v[208:211], v162 offset:3072
	ds_read_b128 v[212:215], v162 offset:4096
	ds_read_b128 v[216:219], v162 offset:5120
	ds_read_b128 v[220:223], v162 offset:6144
	ds_read_b128 v[224:227], v162 offset:7168
	s_waitcnt vmcnt(8)
	s_waitcnt lgkmcnt(0)
	s_barrier
	s_setprio 1
	s_waitcnt lgkmcnt(0)
	v_mfma_f32_16x16x32_bf16 v[124:127], v[142:145], v[196:199], v[124:127]
	v_mfma_f32_16x16x32_bf16 v[120:123], v[168:171], v[196:199], v[120:123]
	v_mfma_f32_16x16x32_bf16 v[108:111], v[142:145], v[204:207], v[108:111]
	v_mfma_f32_16x16x32_bf16 v[104:107], v[168:171], v[204:207], v[104:107]
	v_mfma_f32_16x16x32_bf16 v[92:95], v[142:145], v[212:215], v[92:95]
	v_mfma_f32_16x16x32_bf16 v[88:91], v[168:171], v[212:215], v[88:91]
	v_mfma_f32_16x16x32_bf16 v[76:79], v[142:145], v[220:223], v[76:79]
	v_mfma_f32_16x16x32_bf16 v[72:75], v[168:171], v[220:223], v[72:75]
	v_mfma_f32_16x16x32_bf16 v[124:127], v[146:149], v[200:203], v[124:127]
	v_mfma_f32_16x16x32_bf16 v[120:123], v[172:175], v[200:203], v[120:123]
	v_mfma_f32_16x16x32_bf16 v[108:111], v[146:149], v[208:211], v[108:111]
	v_mfma_f32_16x16x32_bf16 v[104:107], v[172:175], v[208:211], v[104:107]
	v_mfma_f32_16x16x32_bf16 v[92:95], v[146:149], v[216:219], v[92:95]
	v_mfma_f32_16x16x32_bf16 v[88:91], v[172:175], v[216:219], v[88:91]
	v_mfma_f32_16x16x32_bf16 v[76:79], v[146:149], v[224:227], v[76:79]
	v_mfma_f32_16x16x32_bf16 v[72:75], v[172:175], v[224:227], v[72:75]
	s_setprio 0
	s_setprio 1
	v_mfma_f32_16x16x32_bf16 v[116:119], v[176:179], v[196:199], v[116:119]
	v_mfma_f32_16x16x32_bf16 v[112:115], v[184:187], v[196:199], v[112:115]
	v_mfma_f32_16x16x32_bf16 v[100:103], v[176:179], v[204:207], v[100:103]
	v_mfma_f32_16x16x32_bf16 v[96:99], v[184:187], v[204:207], v[96:99]
	v_mfma_f32_16x16x32_bf16 v[84:87], v[176:179], v[212:215], v[84:87]
	v_mfma_f32_16x16x32_bf16 v[80:83], v[184:187], v[212:215], v[80:83]
	v_mfma_f32_16x16x32_bf16 v[68:71], v[176:179], v[220:223], v[68:71]
	v_mfma_f32_16x16x32_bf16 v[64:67], v[184:187], v[220:223], v[64:67]
	v_mfma_f32_16x16x32_bf16 v[116:119], v[180:183], v[200:203], v[116:119]
	v_mfma_f32_16x16x32_bf16 v[112:115], v[188:191], v[200:203], v[112:115]
	v_mfma_f32_16x16x32_bf16 v[100:103], v[180:183], v[208:211], v[100:103]
	v_mfma_f32_16x16x32_bf16 v[96:99], v[188:191], v[208:211], v[96:99]
	v_mfma_f32_16x16x32_bf16 v[84:87], v[180:183], v[216:219], v[84:87]
	v_mfma_f32_16x16x32_bf16 v[80:83], v[188:191], v[216:219], v[80:83]
	v_mfma_f32_16x16x32_bf16 v[68:71], v[180:183], v[224:227], v[68:71]
	v_mfma_f32_16x16x32_bf16 v[64:67], v[188:191], v[224:227], v[64:67]
	s_setprio 0
	s_barrier
	s_add_i32 s61, s41, s3
	s_mov_b32 m0, s61
	s_nop 0
	global_load_lds_dwordx4 v128, s[26:27]
	s_add_i32 m0, s61, 0x2000
	s_add_u32 s62, s26, 0x4000
	s_addc_u32 s63, s27, 0
	s_add_i32 s61, s42, s3
	global_load_lds_dwordx4 v130, s[26:27]
	s_mov_b32 m0, s61
	s_nop 0
	global_load_lds_dwordx4 v128, s[62:63]
	s_add_i32 m0, s61, 0x2000
	s_nop 0
	global_load_lds_dwordx4 v130, s[62:63]
	s_mov_b32 m0, s21
	s_nop 0
	global_load_lds_dwordx4 v128, s[28:29]
	s_mov_b32 m0, s30
	s_nop 0
	global_load_lds_dwordx4 v130, s[28:29]
	ds_read_b128 v[196:199], v162 offset:16384
	ds_read_b128 v[200:203], v162 offset:17408
	ds_read_b128 v[204:207], v162 offset:18432
	ds_read_b128 v[208:211], v162 offset:19456
	ds_read_b128 v[212:215], v162 offset:20480
	ds_read_b128 v[216:219], v162 offset:21504
	ds_read_b128 v[220:223], v162 offset:22528
	ds_read_b128 v[224:227], v162 offset:23552
	s_waitcnt vmcnt(8)
	s_waitcnt lgkmcnt(0)
	s_barrier
	s_setprio 1
	s_waitcnt lgkmcnt(0)
	v_mfma_f32_16x16x32_bf16 v[60:63], v[142:145], v[196:199], v[60:63]
	v_mfma_f32_16x16x32_bf16 v[56:59], v[168:171], v[196:199], v[56:59]
	v_mfma_f32_16x16x32_bf16 v[44:47], v[142:145], v[204:207], v[44:47]
	v_mfma_f32_16x16x32_bf16 v[40:43], v[168:171], v[204:207], v[40:43]
	v_mfma_f32_16x16x32_bf16 v[28:31], v[142:145], v[212:215], v[28:31]
	v_mfma_f32_16x16x32_bf16 v[24:27], v[168:171], v[212:215], v[24:27]
	v_mfma_f32_16x16x32_bf16 v[12:15], v[142:145], v[220:223], v[12:15]
	v_mfma_f32_16x16x32_bf16 v[8:11], v[168:171], v[220:223], v[8:11]
	v_mfma_f32_16x16x32_bf16 v[60:63], v[146:149], v[200:203], v[60:63]
	v_mfma_f32_16x16x32_bf16 v[56:59], v[172:175], v[200:203], v[56:59]
	v_mfma_f32_16x16x32_bf16 v[44:47], v[146:149], v[208:211], v[44:47]
	v_mfma_f32_16x16x32_bf16 v[40:43], v[172:175], v[208:211], v[40:43]
	v_mfma_f32_16x16x32_bf16 v[28:31], v[146:149], v[216:219], v[28:31]
	v_mfma_f32_16x16x32_bf16 v[24:27], v[172:175], v[216:219], v[24:27]
	v_mfma_f32_16x16x32_bf16 v[12:15], v[146:149], v[224:227], v[12:15]
	v_mfma_f32_16x16x32_bf16 v[8:11], v[172:175], v[224:227], v[8:11]
	s_setprio 0
	s_setprio 1
	v_mfma_f32_16x16x32_bf16 v[52:55], v[176:179], v[196:199], v[52:55]
	v_mfma_f32_16x16x32_bf16 v[48:51], v[184:187], v[196:199], v[48:51]
	v_mfma_f32_16x16x32_bf16 v[36:39], v[176:179], v[204:207], v[36:39]
	v_mfma_f32_16x16x32_bf16 v[32:35], v[184:187], v[204:207], v[32:35]
	v_mfma_f32_16x16x32_bf16 v[20:23], v[176:179], v[212:215], v[20:23]
	v_mfma_f32_16x16x32_bf16 v[16:19], v[184:187], v[212:215], v[16:19]
	v_mfma_f32_16x16x32_bf16 v[4:7], v[176:179], v[220:223], v[4:7]
	v_mfma_f32_16x16x32_bf16 v[0:3], v[184:187], v[220:223], v[0:3]
	v_mfma_f32_16x16x32_bf16 v[52:55], v[180:183], v[200:203], v[52:55]
	v_mfma_f32_16x16x32_bf16 v[48:51], v[188:191], v[200:203], v[48:51]
	v_mfma_f32_16x16x32_bf16 v[36:39], v[180:183], v[208:211], v[36:39]
	v_mfma_f32_16x16x32_bf16 v[32:35], v[188:191], v[208:211], v[32:35]
	v_mfma_f32_16x16x32_bf16 v[20:23], v[180:183], v[216:219], v[20:23]
	v_mfma_f32_16x16x32_bf16 v[16:19], v[188:191], v[216:219], v[16:19]
	v_mfma_f32_16x16x32_bf16 v[4:7], v[180:183], v[224:227], v[4:7]
	v_mfma_f32_16x16x32_bf16 v[0:3], v[188:191], v[224:227], v[0:3]
	s_setprio 0
	s_barrier
	s_add_i32 s61, 0, 0x18000
	v_add_u32_e32 v132, s61, v135
	s_add_i32 s62, 0, 0x1c000
	ds_read_b128 v[142:145], v132
	ds_read_b128 v[146:149], v132 offset:1024
	ds_read_b128 v[168:171], v132 offset:2048
	ds_read_b128 v[172:175], v132 offset:3072
	v_add_u32_e32 v132, s62, v135
	ds_read_b128 v[176:179], v132
	ds_read_b128 v[180:183], v132 offset:1024
	ds_read_b128 v[184:187], v132 offset:2048
	ds_read_b128 v[188:191], v132 offset:3072
	s_add_u32 s28, s28, 0x4000
	s_addc_u32 s29, s29, 0
	s_mov_b32 m0, s31
	s_nop 0
	global_load_lds_dwordx4 v128, s[28:29]
	s_mov_b32 m0, s33
	s_nop 0
	global_load_lds_dwordx4 v130, s[28:29]
	ds_read_b128 v[196:199], v162 offset:32768
	ds_read_b128 v[200:203], v162 offset:33792
	ds_read_b128 v[204:207], v162 offset:34816
	ds_read_b128 v[208:211], v162 offset:35840
	ds_read_b128 v[212:215], v162 offset:36864
	ds_read_b128 v[216:219], v162 offset:37888
	ds_read_b128 v[220:223], v162 offset:38912
	ds_read_b128 v[224:227], v162 offset:39936
	s_waitcnt vmcnt(8)
	s_waitcnt lgkmcnt(0)
	s_barrier
	s_setprio 1
	s_waitcnt lgkmcnt(0)
	v_mfma_f32_16x16x32_bf16 v[124:127], v[142:145], v[196:199], v[124:127]
	v_mfma_f32_16x16x32_bf16 v[120:123], v[168:171], v[196:199], v[120:123]
	v_mfma_f32_16x16x32_bf16 v[108:111], v[142:145], v[204:207], v[108:111]
	v_mfma_f32_16x16x32_bf16 v[104:107], v[168:171], v[204:207], v[104:107]
	v_mfma_f32_16x16x32_bf16 v[92:95], v[142:145], v[212:215], v[92:95]
	v_mfma_f32_16x16x32_bf16 v[88:91], v[168:171], v[212:215], v[88:91]
	v_mfma_f32_16x16x32_bf16 v[76:79], v[142:145], v[220:223], v[76:79]
	v_mfma_f32_16x16x32_bf16 v[72:75], v[168:171], v[220:223], v[72:75]
	v_mfma_f32_16x16x32_bf16 v[124:127], v[146:149], v[200:203], v[124:127]
	v_mfma_f32_16x16x32_bf16 v[120:123], v[172:175], v[200:203], v[120:123]
	v_mfma_f32_16x16x32_bf16 v[108:111], v[146:149], v[208:211], v[108:111]
	v_mfma_f32_16x16x32_bf16 v[104:107], v[172:175], v[208:211], v[104:107]
	v_mfma_f32_16x16x32_bf16 v[92:95], v[146:149], v[216:219], v[92:95]
	v_mfma_f32_16x16x32_bf16 v[88:91], v[172:175], v[216:219], v[88:91]
	v_mfma_f32_16x16x32_bf16 v[76:79], v[146:149], v[224:227], v[76:79]
	v_mfma_f32_16x16x32_bf16 v[72:75], v[172:175], v[224:227], v[72:75]
	s_setprio 0
	s_setprio 1
	v_mfma_f32_16x16x32_bf16 v[116:119], v[176:179], v[196:199], v[116:119]
	v_mfma_f32_16x16x32_bf16 v[112:115], v[184:187], v[196:199], v[112:115]
	v_mfma_f32_16x16x32_bf16 v[100:103], v[176:179], v[204:207], v[100:103]
	v_mfma_f32_16x16x32_bf16 v[96:99], v[184:187], v[204:207], v[96:99]
	v_mfma_f32_16x16x32_bf16 v[84:87], v[176:179], v[212:215], v[84:87]
	v_mfma_f32_16x16x32_bf16 v[80:83], v[184:187], v[212:215], v[80:83]
	v_mfma_f32_16x16x32_bf16 v[68:71], v[176:179], v[220:223], v[68:71]
	v_mfma_f32_16x16x32_bf16 v[64:67], v[184:187], v[220:223], v[64:67]
	v_mfma_f32_16x16x32_bf16 v[116:119], v[180:183], v[200:203], v[116:119]
	v_mfma_f32_16x16x32_bf16 v[112:115], v[188:191], v[200:203], v[112:115]
	v_mfma_f32_16x16x32_bf16 v[100:103], v[180:183], v[208:211], v[100:103]
	v_mfma_f32_16x16x32_bf16 v[96:99], v[188:191], v[208:211], v[96:99]
	v_mfma_f32_16x16x32_bf16 v[84:87], v[180:183], v[216:219], v[84:87]
	v_mfma_f32_16x16x32_bf16 v[80:83], v[188:191], v[216:219], v[80:83]
	v_mfma_f32_16x16x32_bf16 v[68:71], v[180:183], v[224:227], v[68:71]
	v_mfma_f32_16x16x32_bf16 v[64:67], v[188:191], v[224:227], v[64:67]
	s_setprio 0
	s_barrier
	s_add_u32 s28, s26, 0x8000
	s_addc_u32 s29, s27, 0
	s_add_i32 s61, s61, s3
	s_mov_b32 m0, s61
	s_nop 0
	global_load_lds_dwordx4 v128, s[28:29]
	s_add_i32 m0, s61, 0x2000
	s_add_u32 s26, s26, 0xc000
	s_addc_u32 s27, s27, 0
	global_load_lds_dwordx4 v130, s[28:29]
	s_add_i32 s28, s62, s3
	s_mov_b32 m0, s28
	s_nop 0
	global_load_lds_dwordx4 v128, s[26:27]
	s_add_i32 m0, s28, 0x2000
	s_nop 0
	global_load_lds_dwordx4 v130, s[26:27]
	s_mov_b32 m0, s37
	s_nop 0
	global_load_lds_dwordx4 v128, s[24:25]
	s_mov_b32 m0, s38
	s_nop 0
	global_load_lds_dwordx4 v130, s[24:25]
	ds_read_b128 v[196:199], v162 offset:49152
	ds_read_b128 v[200:203], v162 offset:50176
	ds_read_b128 v[204:207], v162 offset:51200
	ds_read_b128 v[208:211], v162 offset:52224
	ds_read_b128 v[212:215], v162 offset:53248
	ds_read_b128 v[216:219], v162 offset:54272
	ds_read_b128 v[220:223], v162 offset:55296
	ds_read_b128 v[224:227], v162 offset:56320
	s_waitcnt vmcnt(8)
	s_waitcnt lgkmcnt(0)
	s_barrier
	s_setprio 1
	s_waitcnt lgkmcnt(0)
	v_mfma_f32_16x16x32_bf16 v[60:63], v[142:145], v[196:199], v[60:63]
	v_mfma_f32_16x16x32_bf16 v[56:59], v[168:171], v[196:199], v[56:59]
	v_mfma_f32_16x16x32_bf16 v[44:47], v[142:145], v[204:207], v[44:47]
	v_mfma_f32_16x16x32_bf16 v[40:43], v[168:171], v[204:207], v[40:43]
	v_mfma_f32_16x16x32_bf16 v[28:31], v[142:145], v[212:215], v[28:31]
	v_mfma_f32_16x16x32_bf16 v[24:27], v[168:171], v[212:215], v[24:27]
	v_mfma_f32_16x16x32_bf16 v[12:15], v[142:145], v[220:223], v[12:15]
	v_mfma_f32_16x16x32_bf16 v[8:11], v[168:171], v[220:223], v[8:11]
	v_mfma_f32_16x16x32_bf16 v[60:63], v[146:149], v[200:203], v[60:63]
	v_mfma_f32_16x16x32_bf16 v[56:59], v[172:175], v[200:203], v[56:59]
	v_mfma_f32_16x16x32_bf16 v[44:47], v[146:149], v[208:211], v[44:47]
	v_mfma_f32_16x16x32_bf16 v[40:43], v[172:175], v[208:211], v[40:43]
	v_mfma_f32_16x16x32_bf16 v[28:31], v[146:149], v[216:219], v[28:31]
	v_mfma_f32_16x16x32_bf16 v[24:27], v[172:175], v[216:219], v[24:27]
	v_mfma_f32_16x16x32_bf16 v[12:15], v[146:149], v[224:227], v[12:15]
	v_mfma_f32_16x16x32_bf16 v[8:11], v[172:175], v[224:227], v[8:11]
	s_setprio 0
	s_setprio 1
	v_mfma_f32_16x16x32_bf16 v[52:55], v[176:179], v[196:199], v[52:55]
	v_mfma_f32_16x16x32_bf16 v[48:51], v[184:187], v[196:199], v[48:51]
	v_mfma_f32_16x16x32_bf16 v[36:39], v[176:179], v[204:207], v[36:39]
	v_mfma_f32_16x16x32_bf16 v[32:35], v[184:187], v[204:207], v[32:35]
	v_mfma_f32_16x16x32_bf16 v[20:23], v[176:179], v[212:215], v[20:23]
	v_mfma_f32_16x16x32_bf16 v[16:19], v[184:187], v[212:215], v[16:19]
	v_mfma_f32_16x16x32_bf16 v[4:7], v[176:179], v[220:223], v[4:7]
	v_mfma_f32_16x16x32_bf16 v[0:3], v[184:187], v[220:223], v[0:3]
	v_mfma_f32_16x16x32_bf16 v[52:55], v[180:183], v[200:203], v[52:55]
	v_mfma_f32_16x16x32_bf16 v[48:51], v[188:191], v[200:203], v[48:51]
	v_mfma_f32_16x16x32_bf16 v[36:39], v[180:183], v[208:211], v[36:39]
	v_mfma_f32_16x16x32_bf16 v[32:35], v[188:191], v[208:211], v[32:35]
	v_mfma_f32_16x16x32_bf16 v[20:23], v[180:183], v[216:219], v[20:23]
	v_mfma_f32_16x16x32_bf16 v[16:19], v[188:191], v[216:219], v[16:19]
	v_mfma_f32_16x16x32_bf16 v[4:7], v[180:183], v[224:227], v[4:7]
	v_mfma_f32_16x16x32_bf16 v[0:3], v[188:191], v[224:227], v[0:3]
	s_setprio 0
	s_barrier
	s_add_i32 s60, s60, 2
	s_add_u32 s22, s22, 0x10000
	s_addc_u32 s23, s23, 0
	s_add_u32 s48, s48, 0x10000
	s_addc_u32 s49, s49, 0
	s_cmp_gt_u32 s60, 61
	s_cbranch_scc0 .LBB0_94
	s_and_b64 vcc, exec, s[10:11]
	s_cbranch_vccz .LBB0_97
	s_barrier

.LBB0_373:
	ds_read_b128 v[128:131], v164
	ds_read_b128 v[132:135], v164 offset:1024
	ds_read_b128 v[136:139], v164 offset:2048
	ds_read_b128 v[140:143], v164 offset:3072
	ds_read_b128 v[154:157], v166
	ds_read_b128 v[170:173], v166 offset:1024
	ds_read_b128 v[174:177], v166 offset:2048
	ds_read_b128 v[178:181], v166 offset:3072
	s_add_u32 s30, s28, 0x4000
	s_addc_u32 s31, s29, 0
	s_cmp_eq_u32 s49, 60
	s_cselect_b32 s36, s13, s30
	s_cselect_b32 s37, s2, s31
	s_cselect_b32 s34, s21, s27
	s_cselect_b32 s35, s19, s48
	s_add_u32 s30, s36, 0x8000
	s_addc_u32 s31, s37, 0
	s_add_i32 m0, s33, 0xc000
	s_nop 0
	global_load_lds_dwordx4 v144, s[28:29]
	s_add_i32 m0, s33, 0xe000
	s_nop 0
	global_load_lds_dwordx4 v146, s[28:29]
	ds_read_b128 v[182:185], v168
	ds_read_b128 v[186:189], v168 offset:1024
	ds_read_b128 v[190:193], v168 offset:2048
	ds_read_b128 v[196:199], v168 offset:3072
	ds_read_b128 v[200:203], v168 offset:4096
	ds_read_b128 v[204:207], v168 offset:5120
	ds_read_b128 v[208:211], v168 offset:6144
	ds_read_b128 v[212:215], v168 offset:7168
	s_waitcnt vmcnt(8)
	s_waitcnt lgkmcnt(0)
	s_barrier
	s_setprio 1
	s_waitcnt lgkmcnt(0)
	v_mfma_f32_16x16x32_bf16 v[124:127], v[128:131], v[182:185], v[124:127]
	v_mfma_f32_16x16x32_bf16 v[120:123], v[136:139], v[182:185], v[120:123]
	v_mfma_f32_16x16x32_bf16 v[108:111], v[128:131], v[190:193], v[108:111]
	v_mfma_f32_16x16x32_bf16 v[104:107], v[136:139], v[190:193], v[104:107]
	v_mfma_f32_16x16x32_bf16 v[92:95], v[128:131], v[200:203], v[92:95]
	v_mfma_f32_16x16x32_bf16 v[88:91], v[136:139], v[200:203], v[88:91]
	v_mfma_f32_16x16x32_bf16 v[76:79], v[128:131], v[208:211], v[76:79]
	v_mfma_f32_16x16x32_bf16 v[72:75], v[136:139], v[208:211], v[72:75]
	v_mfma_f32_16x16x32_bf16 v[124:127], v[132:135], v[186:189], v[124:127]
	v_mfma_f32_16x16x32_bf16 v[120:123], v[140:143], v[186:189], v[120:123]
	v_mfma_f32_16x16x32_bf16 v[108:111], v[132:135], v[196:199], v[108:111]
	v_mfma_f32_16x16x32_bf16 v[104:107], v[140:143], v[196:199], v[104:107]
	v_mfma_f32_16x16x32_bf16 v[92:95], v[132:135], v[204:207], v[92:95]
	v_mfma_f32_16x16x32_bf16 v[88:91], v[140:143], v[204:207], v[88:91]
	v_mfma_f32_16x16x32_bf16 v[76:79], v[132:135], v[212:215], v[76:79]
	v_mfma_f32_16x16x32_bf16 v[72:75], v[140:143], v[212:215], v[72:75]
	s_setprio 0
	s_setprio 1
	v_mfma_f32_16x16x32_bf16 v[116:119], v[154:157], v[182:185], v[116:119]
	v_mfma_f32_16x16x32_bf16 v[112:115], v[174:177], v[182:185], v[112:115]
	v_mfma_f32_16x16x32_bf16 v[100:103], v[154:157], v[190:193], v[100:103]
	v_mfma_f32_16x16x32_bf16 v[96:99], v[174:177], v[190:193], v[96:99]
	v_mfma_f32_16x16x32_bf16 v[84:87], v[154:157], v[200:203], v[84:87]
	v_mfma_f32_16x16x32_bf16 v[80:83], v[174:177], v[200:203], v[80:83]
	v_mfma_f32_16x16x32_bf16 v[68:71], v[154:157], v[208:211], v[68:71]
	v_mfma_f32_16x16x32_bf16 v[64:67], v[174:177], v[208:211], v[64:67]
	v_mfma_f32_16x16x32_bf16 v[116:119], v[170:173], v[186:189], v[116:119]
	v_mfma_f32_16x16x32_bf16 v[112:115], v[178:181], v[186:189], v[112:115]
	v_mfma_f32_16x16x32_bf16 v[100:103], v[170:173], v[196:199], v[100:103]
	v_mfma_f32_16x16x32_bf16 v[96:99], v[178:181], v[196:199], v[96:99]
	v_mfma_f32_16x16x32_bf16 v[84:87], v[170:173], v[204:207], v[84:87]
	v_mfma_f32_16x16x32_bf16 v[80:83], v[178:181], v[204:207], v[80:83]
	v_mfma_f32_16x16x32_bf16 v[68:71], v[170:173], v[212:215], v[68:71]
	v_mfma_f32_16x16x32_bf16 v[64:67], v[178:181], v[212:215], v[64:67]
	s_setprio 0
	s_barrier
	s_add_i32 s61, s57, s3
	s_mov_b32 m0, s61
	s_nop 0
	global_load_lds_dwordx4 v144, s[34:35]
	s_add_i32 m0, s61, 0x2000
	s_add_u32 s62, s34, 0x4000
	s_addc_u32 s63, s35, 0
	s_add_i32 s61, s60, s3
	global_load_lds_dwordx4 v146, s[34:35]
	s_mov_b32 m0, s61
	s_nop 0
	global_load_lds_dwordx4 v144, s[62:63]
	s_add_i32 m0, s61, 0x2000
	s_nop 0
	global_load_lds_dwordx4 v146, s[62:63]
	s_mov_b32 m0, s33
	s_nop 0
	global_load_lds_dwordx4 v144, s[36:37]
	s_mov_b32 m0, s38
	s_nop 0
	global_load_lds_dwordx4 v146, s[36:37]
	ds_read_b128 v[182:185], v168 offset:16384
	ds_read_b128 v[186:189], v168 offset:17408
	ds_read_b128 v[190:193], v168 offset:18432
	ds_read_b128 v[196:199], v168 offset:19456
	ds_read_b128 v[200:203], v168 offset:20480
	ds_read_b128 v[204:207], v168 offset:21504
	ds_read_b128 v[208:211], v168 offset:22528
	ds_read_b128 v[212:215], v168 offset:23552
	s_waitcnt vmcnt(8)
	s_waitcnt lgkmcnt(0)
	s_barrier
	s_setprio 1
	s_waitcnt lgkmcnt(0)
	v_mfma_f32_16x16x32_bf16 v[60:63], v[128:131], v[182:185], v[60:63]
	v_mfma_f32_16x16x32_bf16 v[56:59], v[136:139], v[182:185], v[56:59]
	v_mfma_f32_16x16x32_bf16 v[44:47], v[128:131], v[190:193], v[44:47]
	v_mfma_f32_16x16x32_bf16 v[40:43], v[136:139], v[190:193], v[40:43]
	v_mfma_f32_16x16x32_bf16 v[28:31], v[128:131], v[200:203], v[28:31]
	v_mfma_f32_16x16x32_bf16 v[24:27], v[136:139], v[200:203], v[24:27]
	v_mfma_f32_16x16x32_bf16 v[12:15], v[128:131], v[208:211], v[12:15]
	v_mfma_f32_16x16x32_bf16 v[8:11], v[136:139], v[208:211], v[8:11]
	v_mfma_f32_16x16x32_bf16 v[60:63], v[132:135], v[186:189], v[60:63]
	v_mfma_f32_16x16x32_bf16 v[56:59], v[140:143], v[186:189], v[56:59]
	v_mfma_f32_16x16x32_bf16 v[44:47], v[132:135], v[196:199], v[44:47]
	v_mfma_f32_16x16x32_bf16 v[40:43], v[140:143], v[196:199], v[40:43]
	v_mfma_f32_16x16x32_bf16 v[28:31], v[132:135], v[204:207], v[28:31]
	v_mfma_f32_16x16x32_bf16 v[24:27], v[140:143], v[204:207], v[24:27]
	v_mfma_f32_16x16x32_bf16 v[12:15], v[132:135], v[212:215], v[12:15]
	v_mfma_f32_16x16x32_bf16 v[8:11], v[140:143], v[212:215], v[8:11]
	s_setprio 0
	s_setprio 1
	v_mfma_f32_16x16x32_bf16 v[52:55], v[154:157], v[182:185], v[52:55]
	v_mfma_f32_16x16x32_bf16 v[48:51], v[174:177], v[182:185], v[48:51]
	v_mfma_f32_16x16x32_bf16 v[36:39], v[154:157], v[190:193], v[36:39]
	v_mfma_f32_16x16x32_bf16 v[32:35], v[174:177], v[190:193], v[32:35]
	v_mfma_f32_16x16x32_bf16 v[20:23], v[154:157], v[200:203], v[20:23]
	v_mfma_f32_16x16x32_bf16 v[16:19], v[174:177], v[200:203], v[16:19]
	v_mfma_f32_16x16x32_bf16 v[4:7], v[154:157], v[208:211], v[4:7]
	v_mfma_f32_16x16x32_bf16 v[0:3], v[174:177], v[208:211], v[0:3]
	v_mfma_f32_16x16x32_bf16 v[52:55], v[170:173], v[186:189], v[52:55]
	v_mfma_f32_16x16x32_bf16 v[48:51], v[178:181], v[186:189], v[48:51]
	v_mfma_f32_16x16x32_bf16 v[36:39], v[170:173], v[196:199], v[36:39]
	v_mfma_f32_16x16x32_bf16 v[32:35], v[178:181], v[196:199], v[32:35]
	v_mfma_f32_16x16x32_bf16 v[20:23], v[170:173], v[204:207], v[20:23]
	v_mfma_f32_16x16x32_bf16 v[16:19], v[178:181], v[204:207], v[16:19]
	v_mfma_f32_16x16x32_bf16 v[4:7], v[170:173], v[212:215], v[4:7]
	v_mfma_f32_16x16x32_bf16 v[0:3], v[178:181], v[212:215], v[0:3]
	s_setprio 0
	s_barrier
	s_add_i32 s61, 0, 0x18000
	s_add_i32 s62, 0, 0x1c000
	v_add_u32_e32 v140, s61, v162
	v_add_u32_e32 v148, s62, v162
	ds_read_b128 v[128:131], v140
	ds_read_b128 v[132:135], v140 offset:1024
	ds_read_b128 v[136:139], v140 offset:2048
	ds_read_b128 v[140:143], v140 offset:3072
	ds_read_b128 v[154:157], v148
	ds_read_b128 v[170:173], v148 offset:1024
	ds_read_b128 v[174:177], v148 offset:2048
	ds_read_b128 v[178:181], v148 offset:3072
	s_add_u32 s36, s36, 0x4000
	s_addc_u32 s37, s37, 0
	s_mov_b32 m0, s39
	s_nop 0
	global_load_lds_dwordx4 v144, s[36:37]
	s_mov_b32 m0, s40
	s_nop 0
	global_load_lds_dwordx4 v146, s[36:37]
	ds_read_b128 v[182:185], v168 offset:32768
	ds_read_b128 v[186:189], v168 offset:33792
	ds_read_b128 v[190:193], v168 offset:34816
	ds_read_b128 v[196:199], v168 offset:35840
	ds_read_b128 v[200:203], v168 offset:36864
	ds_read_b128 v[204:207], v168 offset:37888
	ds_read_b128 v[208:211], v168 offset:38912
	ds_read_b128 v[212:215], v168 offset:39936
	s_waitcnt vmcnt(8)
	s_waitcnt lgkmcnt(0)
	s_barrier
	s_setprio 1
	s_waitcnt lgkmcnt(0)
	v_mfma_f32_16x16x32_bf16 v[124:127], v[128:131], v[182:185], v[124:127]
	v_mfma_f32_16x16x32_bf16 v[120:123], v[136:139], v[182:185], v[120:123]
	v_mfma_f32_16x16x32_bf16 v[108:111], v[128:131], v[190:193], v[108:111]
	v_mfma_f32_16x16x32_bf16 v[104:107], v[136:139], v[190:193], v[104:107]
	v_mfma_f32_16x16x32_bf16 v[92:95], v[128:131], v[200:203], v[92:95]
	v_mfma_f32_16x16x32_bf16 v[88:91], v[136:139], v[200:203], v[88:91]
	v_mfma_f32_16x16x32_bf16 v[76:79], v[128:131], v[208:211], v[76:79]
	v_mfma_f32_16x16x32_bf16 v[72:75], v[136:139], v[208:211], v[72:75]
	v_mfma_f32_16x16x32_bf16 v[124:127], v[132:135], v[186:189], v[124:127]
	v_mfma_f32_16x16x32_bf16 v[120:123], v[140:143], v[186:189], v[120:123]
	v_mfma_f32_16x16x32_bf16 v[108:111], v[132:135], v[196:199], v[108:111]
	v_mfma_f32_16x16x32_bf16 v[104:107], v[140:143], v[196:199], v[104:107]
	v_mfma_f32_16x16x32_bf16 v[92:95], v[132:135], v[204:207], v[92:95]
	v_mfma_f32_16x16x32_bf16 v[88:91], v[140:143], v[204:207], v[88:91]
	v_mfma_f32_16x16x32_bf16 v[76:79], v[132:135], v[212:215], v[76:79]
	v_mfma_f32_16x16x32_bf16 v[72:75], v[140:143], v[212:215], v[72:75]
	s_setprio 0
	s_setprio 1
	v_mfma_f32_16x16x32_bf16 v[116:119], v[154:157], v[182:185], v[116:119]
	v_mfma_f32_16x16x32_bf16 v[112:115], v[174:177], v[182:185], v[112:115]
	v_mfma_f32_16x16x32_bf16 v[100:103], v[154:157], v[190:193], v[100:103]
	v_mfma_f32_16x16x32_bf16 v[96:99], v[174:177], v[190:193], v[96:99]
	v_mfma_f32_16x16x32_bf16 v[84:87], v[154:157], v[200:203], v[84:87]
	v_mfma_f32_16x16x32_bf16 v[80:83], v[174:177], v[200:203], v[80:83]
	v_mfma_f32_16x16x32_bf16 v[68:71], v[154:157], v[208:211], v[68:71]
	v_mfma_f32_16x16x32_bf16 v[64:67], v[174:177], v[208:211], v[64:67]
	v_mfma_f32_16x16x32_bf16 v[116:119], v[170:173], v[186:189], v[116:119]
	v_mfma_f32_16x16x32_bf16 v[112:115], v[178:181], v[186:189], v[112:115]
	v_mfma_f32_16x16x32_bf16 v[100:103], v[170:173], v[196:199], v[100:103]
	v_mfma_f32_16x16x32_bf16 v[96:99], v[178:181], v[196:199], v[96:99]
	v_mfma_f32_16x16x32_bf16 v[84:87], v[170:173], v[204:207], v[84:87]
	v_mfma_f32_16x16x32_bf16 v[80:83], v[178:181], v[204:207], v[80:83]
	v_mfma_f32_16x16x32_bf16 v[68:71], v[170:173], v[212:215], v[68:71]
	v_mfma_f32_16x16x32_bf16 v[64:67], v[178:181], v[212:215], v[64:67]
	s_setprio 0
	s_barrier
	s_add_u32 s36, s34, 0x8000
	s_addc_u32 s37, s35, 0
	s_add_i32 s61, s61, s3
	s_mov_b32 m0, s61
	s_nop 0
	global_load_lds_dwordx4 v144, s[36:37]
	s_add_i32 m0, s61, 0x2000
	s_add_u32 s34, s34, 0xc000
	s_addc_u32 s35, s35, 0
	global_load_lds_dwordx4 v146, s[36:37]
	s_add_i32 s36, s62, s3
	s_mov_b32 m0, s36
	s_nop 0
	global_load_lds_dwordx4 v144, s[34:35]
	s_add_i32 m0, s36, 0x2000
	s_nop 0
	global_load_lds_dwordx4 v146, s[34:35]
	s_mov_b32 m0, s46
	s_nop 0
	global_load_lds_dwordx4 v144, s[30:31]
	s_mov_b32 m0, s47
	s_nop 0
	global_load_lds_dwordx4 v146, s[30:31]
	ds_read_b128 v[182:185], v168 offset:49152
	ds_read_b128 v[186:189], v168 offset:50176
	ds_read_b128 v[190:193], v168 offset:51200
	ds_read_b128 v[196:199], v168 offset:52224
	ds_read_b128 v[200:203], v168 offset:53248
	ds_read_b128 v[204:207], v168 offset:54272
	ds_read_b128 v[208:211], v168 offset:55296
	ds_read_b128 v[212:215], v168 offset:56320
	s_waitcnt vmcnt(8)
	s_waitcnt lgkmcnt(0)
	s_barrier
	s_setprio 1
	s_waitcnt lgkmcnt(0)
	v_mfma_f32_16x16x32_bf16 v[60:63], v[128:131], v[182:185], v[60:63]
	v_mfma_f32_16x16x32_bf16 v[56:59], v[136:139], v[182:185], v[56:59]
	v_mfma_f32_16x16x32_bf16 v[44:47], v[128:131], v[190:193], v[44:47]
	v_mfma_f32_16x16x32_bf16 v[40:43], v[136:139], v[190:193], v[40:43]
	v_mfma_f32_16x16x32_bf16 v[28:31], v[128:131], v[200:203], v[28:31]
	v_mfma_f32_16x16x32_bf16 v[24:27], v[136:139], v[200:203], v[24:27]
	v_mfma_f32_16x16x32_bf16 v[12:15], v[128:131], v[208:211], v[12:15]
	v_mfma_f32_16x16x32_bf16 v[8:11], v[136:139], v[208:211], v[8:11]
	v_mfma_f32_16x16x32_bf16 v[60:63], v[132:135], v[186:189], v[60:63]
	v_mfma_f32_16x16x32_bf16 v[56:59], v[140:143], v[186:189], v[56:59]
	v_mfma_f32_16x16x32_bf16 v[44:47], v[132:135], v[196:199], v[44:47]
	v_mfma_f32_16x16x32_bf16 v[40:43], v[140:143], v[196:199], v[40:43]
	v_mfma_f32_16x16x32_bf16 v[28:31], v[132:135], v[204:207], v[28:31]
	v_mfma_f32_16x16x32_bf16 v[24:27], v[140:143], v[204:207], v[24:27]
	v_mfma_f32_16x16x32_bf16 v[12:15], v[132:135], v[212:215], v[12:15]
	v_mfma_f32_16x16x32_bf16 v[8:11], v[140:143], v[212:215], v[8:11]
	s_setprio 0
	s_setprio 1
	v_mfma_f32_16x16x32_bf16 v[52:55], v[154:157], v[182:185], v[52:55]
	v_mfma_f32_16x16x32_bf16 v[48:51], v[174:177], v[182:185], v[48:51]
	v_mfma_f32_16x16x32_bf16 v[36:39], v[154:157], v[190:193], v[36:39]
	v_mfma_f32_16x16x32_bf16 v[32:35], v[174:177], v[190:193], v[32:35]
	v_mfma_f32_16x16x32_bf16 v[20:23], v[154:157], v[200:203], v[20:23]
	v_mfma_f32_16x16x32_bf16 v[16:19], v[174:177], v[200:203], v[16:19]
	v_mfma_f32_16x16x32_bf16 v[4:7], v[154:157], v[208:211], v[4:7]
	v_mfma_f32_16x16x32_bf16 v[0:3], v[174:177], v[208:211], v[0:3]
	v_mfma_f32_16x16x32_bf16 v[52:55], v[170:173], v[186:189], v[52:55]
	v_mfma_f32_16x16x32_bf16 v[48:51], v[178:181], v[186:189], v[48:51]
	v_mfma_f32_16x16x32_bf16 v[36:39], v[170:173], v[196:199], v[36:39]
	v_mfma_f32_16x16x32_bf16 v[32:35], v[178:181], v[196:199], v[32:35]
	v_mfma_f32_16x16x32_bf16 v[20:23], v[170:173], v[204:207], v[20:23]
	v_mfma_f32_16x16x32_bf16 v[16:19], v[178:181], v[204:207], v[16:19]
	v_mfma_f32_16x16x32_bf16 v[4:7], v[170:173], v[212:215], v[4:7]
	v_mfma_f32_16x16x32_bf16 v[0:3], v[178:181], v[212:215], v[0:3]
	s_setprio 0
	s_barrier
	s_add_i32 s49, s49, 2
	s_add_u32 s28, s28, 0x10000
	s_addc_u32 s29, s29, 0
	s_add_u32 s27, s27, 0x10000
	s_addc_u32 s48, s48, 0
	s_cmp_gt_u32 s49, 61
	s_cbranch_scc0 .LBB0_373
	s_and_b64 vcc, exec, s[16:17]
	s_cbranch_vccz .LBB0_376
	s_barrier

.LBB0_469:
	ds_read_b128 v[128:131], v197
	ds_read_b128 v[132:135], v197 offset:1024
	ds_read_b128 v[136:139], v197 offset:2048
	ds_read_b128 v[140:143], v197 offset:3072
	ds_read_b128 v[144:147], v198
	ds_read_b128 v[148:151], v198 offset:1024
	ds_read_b128 v[152:155], v198 offset:2048
	ds_read_b128 v[156:159], v198 offset:3072
	s_add_u32 s28, s26, 0x4000
	s_addc_u32 s29, s27, 0
	s_cmp_eq_u32 s49, 60
	s_cselect_b32 s34, s2, s28
	s_cselect_b32 s35, s1, s29
	s_cselect_b32 s30, s19, s25
	s_cselect_b32 s31, s17, s48
	s_add_u32 s28, s34, 0x8000
	s_addc_u32 s29, s35, 0
	s_add_i32 m0, s33, 0xc000
	s_nop 0
	global_load_lds_dwordx4 v176, s[26:27]
	s_add_i32 m0, s33, 0xe000
	s_nop 0
	global_load_lds_dwordx4 v178, s[26:27]
	ds_read_b128 v[160:163], v199
	ds_read_b128 v[164:167], v199 offset:1024
	ds_read_b128 v[168:171], v199 offset:2048
	ds_read_b128 v[172:175], v199 offset:3072
	ds_read_b128 v[188:191], v199 offset:4096
	ds_read_b128 v[202:205], v199 offset:5120
	ds_read_b128 v[206:209], v199 offset:6144
	ds_read_b128 v[210:213], v199 offset:7168
	s_waitcnt vmcnt(8)
	s_waitcnt lgkmcnt(0)
	s_barrier
	s_setprio 1
	s_waitcnt lgkmcnt(0)
	v_mfma_f32_16x16x32_bf16 v[124:127], v[128:131], v[160:163], v[124:127]
	v_mfma_f32_16x16x32_bf16 v[120:123], v[136:139], v[160:163], v[120:123]
	v_mfma_f32_16x16x32_bf16 v[108:111], v[128:131], v[168:171], v[108:111]
	v_mfma_f32_16x16x32_bf16 v[104:107], v[136:139], v[168:171], v[104:107]
	v_mfma_f32_16x16x32_bf16 v[92:95], v[128:131], v[188:191], v[92:95]
	v_mfma_f32_16x16x32_bf16 v[88:91], v[136:139], v[188:191], v[88:91]
	v_mfma_f32_16x16x32_bf16 v[76:79], v[128:131], v[206:209], v[76:79]
	v_mfma_f32_16x16x32_bf16 v[72:75], v[136:139], v[206:209], v[72:75]
	v_mfma_f32_16x16x32_bf16 v[124:127], v[132:135], v[164:167], v[124:127]
	v_mfma_f32_16x16x32_bf16 v[120:123], v[140:143], v[164:167], v[120:123]
	v_mfma_f32_16x16x32_bf16 v[108:111], v[132:135], v[172:175], v[108:111]
	v_mfma_f32_16x16x32_bf16 v[104:107], v[140:143], v[172:175], v[104:107]
	v_mfma_f32_16x16x32_bf16 v[92:95], v[132:135], v[202:205], v[92:95]
	v_mfma_f32_16x16x32_bf16 v[88:91], v[140:143], v[202:205], v[88:91]
	v_mfma_f32_16x16x32_bf16 v[76:79], v[132:135], v[210:213], v[76:79]
	v_mfma_f32_16x16x32_bf16 v[72:75], v[140:143], v[210:213], v[72:75]
	s_setprio 0
	s_setprio 1
	v_mfma_f32_16x16x32_bf16 v[116:119], v[144:147], v[160:163], v[116:119]
	v_mfma_f32_16x16x32_bf16 v[112:115], v[152:155], v[160:163], v[112:115]
	v_mfma_f32_16x16x32_bf16 v[100:103], v[144:147], v[168:171], v[100:103]
	v_mfma_f32_16x16x32_bf16 v[96:99], v[152:155], v[168:171], v[96:99]
	v_mfma_f32_16x16x32_bf16 v[84:87], v[144:147], v[188:191], v[84:87]
	v_mfma_f32_16x16x32_bf16 v[80:83], v[152:155], v[188:191], v[80:83]
	v_mfma_f32_16x16x32_bf16 v[68:71], v[144:147], v[206:209], v[68:71]
	v_mfma_f32_16x16x32_bf16 v[64:67], v[152:155], v[206:209], v[64:67]
	v_mfma_f32_16x16x32_bf16 v[116:119], v[148:151], v[164:167], v[116:119]
	v_mfma_f32_16x16x32_bf16 v[112:115], v[156:159], v[164:167], v[112:115]
	v_mfma_f32_16x16x32_bf16 v[100:103], v[148:151], v[172:175], v[100:103]
	v_mfma_f32_16x16x32_bf16 v[96:99], v[156:159], v[172:175], v[96:99]
	v_mfma_f32_16x16x32_bf16 v[84:87], v[148:151], v[202:205], v[84:87]
	v_mfma_f32_16x16x32_bf16 v[80:83], v[156:159], v[202:205], v[80:83]
	v_mfma_f32_16x16x32_bf16 v[68:71], v[148:151], v[210:213], v[68:71]
	v_mfma_f32_16x16x32_bf16 v[64:67], v[156:159], v[210:213], v[64:67]
	s_setprio 0
	s_barrier
	s_add_i32 s50, s46, s3
	s_mov_b32 m0, s50
	s_nop 0
	global_load_lds_dwordx4 v176, s[30:31]
	s_add_i32 m0, s50, 0x2000
	s_add_u32 s50, s30, 0x4000
	s_addc_u32 s51, s31, 0
	s_add_i32 s52, s47, s3
	global_load_lds_dwordx4 v178, s[30:31]
	s_mov_b32 m0, s52
	s_nop 0
	global_load_lds_dwordx4 v176, s[50:51]
	s_add_i32 m0, s52, 0x2000
	s_nop 0
	global_load_lds_dwordx4 v178, s[50:51]
	s_mov_b32 m0, s33
	s_nop 0
	global_load_lds_dwordx4 v176, s[34:35]
	s_mov_b32 m0, s36
	s_nop 0
	global_load_lds_dwordx4 v178, s[34:35]
	ds_read_b128 v[160:163], v199 offset:16384
	ds_read_b128 v[164:167], v199 offset:17408
	ds_read_b128 v[168:171], v199 offset:18432
	ds_read_b128 v[172:175], v199 offset:19456
	ds_read_b128 v[188:191], v199 offset:20480
	ds_read_b128 v[202:205], v199 offset:21504
	ds_read_b128 v[206:209], v199 offset:22528
	ds_read_b128 v[210:213], v199 offset:23552
	s_waitcnt vmcnt(8)
	s_waitcnt lgkmcnt(0)
	s_barrier
	s_setprio 1
	s_waitcnt lgkmcnt(0)
	v_mfma_f32_16x16x32_bf16 v[60:63], v[128:131], v[160:163], v[60:63]
	v_mfma_f32_16x16x32_bf16 v[56:59], v[136:139], v[160:163], v[56:59]
	v_mfma_f32_16x16x32_bf16 v[44:47], v[128:131], v[168:171], v[44:47]
	v_mfma_f32_16x16x32_bf16 v[40:43], v[136:139], v[168:171], v[40:43]
	v_mfma_f32_16x16x32_bf16 v[28:31], v[128:131], v[188:191], v[28:31]
	v_mfma_f32_16x16x32_bf16 v[24:27], v[136:139], v[188:191], v[24:27]
	v_mfma_f32_16x16x32_bf16 v[12:15], v[128:131], v[206:209], v[12:15]
	v_mfma_f32_16x16x32_bf16 v[8:11], v[136:139], v[206:209], v[8:11]
	v_mfma_f32_16x16x32_bf16 v[60:63], v[132:135], v[164:167], v[60:63]
	v_mfma_f32_16x16x32_bf16 v[56:59], v[140:143], v[164:167], v[56:59]
	v_mfma_f32_16x16x32_bf16 v[44:47], v[132:135], v[172:175], v[44:47]
	v_mfma_f32_16x16x32_bf16 v[40:43], v[140:143], v[172:175], v[40:43]
	v_mfma_f32_16x16x32_bf16 v[28:31], v[132:135], v[202:205], v[28:31]
	v_mfma_f32_16x16x32_bf16 v[24:27], v[140:143], v[202:205], v[24:27]
	v_mfma_f32_16x16x32_bf16 v[12:15], v[132:135], v[210:213], v[12:15]
	v_mfma_f32_16x16x32_bf16 v[8:11], v[140:143], v[210:213], v[8:11]
	s_setprio 0
	s_setprio 1
	v_mfma_f32_16x16x32_bf16 v[52:55], v[144:147], v[160:163], v[52:55]
	v_mfma_f32_16x16x32_bf16 v[48:51], v[152:155], v[160:163], v[48:51]
	v_mfma_f32_16x16x32_bf16 v[36:39], v[144:147], v[168:171], v[36:39]
	v_mfma_f32_16x16x32_bf16 v[32:35], v[152:155], v[168:171], v[32:35]
	v_mfma_f32_16x16x32_bf16 v[20:23], v[144:147], v[188:191], v[20:23]
	v_mfma_f32_16x16x32_bf16 v[16:19], v[152:155], v[188:191], v[16:19]
	v_mfma_f32_16x16x32_bf16 v[4:7], v[144:147], v[206:209], v[4:7]
	v_mfma_f32_16x16x32_bf16 v[0:3], v[152:155], v[206:209], v[0:3]
	v_mfma_f32_16x16x32_bf16 v[52:55], v[148:151], v[164:167], v[52:55]
	v_mfma_f32_16x16x32_bf16 v[48:51], v[156:159], v[164:167], v[48:51]
	v_mfma_f32_16x16x32_bf16 v[36:39], v[148:151], v[172:175], v[36:39]
	v_mfma_f32_16x16x32_bf16 v[32:35], v[156:159], v[172:175], v[32:35]
	v_mfma_f32_16x16x32_bf16 v[20:23], v[148:151], v[202:205], v[20:23]
	v_mfma_f32_16x16x32_bf16 v[16:19], v[156:159], v[202:205], v[16:19]
	v_mfma_f32_16x16x32_bf16 v[4:7], v[148:151], v[210:213], v[4:7]
	v_mfma_f32_16x16x32_bf16 v[0:3], v[156:159], v[210:213], v[0:3]
	s_setprio 0
	s_barrier
	s_add_i32 s50, 0, 0x18000
	s_add_i32 s51, 0, 0x1c000
	v_add_u32_e32 v140, s50, v196
	v_add_u32_e32 v156, s51, v196
	ds_read_b128 v[128:131], v140
	ds_read_b128 v[132:135], v140 offset:1024
	ds_read_b128 v[136:139], v140 offset:2048
	ds_read_b128 v[140:143], v140 offset:3072
	ds_read_b128 v[144:147], v156
	ds_read_b128 v[148:151], v156 offset:1024
	ds_read_b128 v[152:155], v156 offset:2048
	ds_read_b128 v[156:159], v156 offset:3072
	s_add_u32 s34, s34, 0x4000
	s_addc_u32 s35, s35, 0
	s_mov_b32 m0, s37
	s_nop 0
	global_load_lds_dwordx4 v176, s[34:35]
	s_mov_b32 m0, s38
	s_nop 0
	global_load_lds_dwordx4 v178, s[34:35]
	ds_read_b128 v[160:163], v199 offset:32768
	ds_read_b128 v[164:167], v199 offset:33792
	ds_read_b128 v[168:171], v199 offset:34816
	ds_read_b128 v[172:175], v199 offset:35840
	ds_read_b128 v[188:191], v199 offset:36864
	ds_read_b128 v[202:205], v199 offset:37888
	ds_read_b128 v[206:209], v199 offset:38912
	ds_read_b128 v[210:213], v199 offset:39936
	s_waitcnt vmcnt(8)
	s_waitcnt lgkmcnt(0)
	s_barrier
	s_setprio 1
	s_waitcnt lgkmcnt(0)
	v_mfma_f32_16x16x32_bf16 v[124:127], v[128:131], v[160:163], v[124:127]
	v_mfma_f32_16x16x32_bf16 v[120:123], v[136:139], v[160:163], v[120:123]
	v_mfma_f32_16x16x32_bf16 v[108:111], v[128:131], v[168:171], v[108:111]
	v_mfma_f32_16x16x32_bf16 v[104:107], v[136:139], v[168:171], v[104:107]
	v_mfma_f32_16x16x32_bf16 v[92:95], v[128:131], v[188:191], v[92:95]
	v_mfma_f32_16x16x32_bf16 v[88:91], v[136:139], v[188:191], v[88:91]
	v_mfma_f32_16x16x32_bf16 v[76:79], v[128:131], v[206:209], v[76:79]
	v_mfma_f32_16x16x32_bf16 v[72:75], v[136:139], v[206:209], v[72:75]
	v_mfma_f32_16x16x32_bf16 v[124:127], v[132:135], v[164:167], v[124:127]
	v_mfma_f32_16x16x32_bf16 v[120:123], v[140:143], v[164:167], v[120:123]
	v_mfma_f32_16x16x32_bf16 v[108:111], v[132:135], v[172:175], v[108:111]
	v_mfma_f32_16x16x32_bf16 v[104:107], v[140:143], v[172:175], v[104:107]
	v_mfma_f32_16x16x32_bf16 v[92:95], v[132:135], v[202:205], v[92:95]
	v_mfma_f32_16x16x32_bf16 v[88:91], v[140:143], v[202:205], v[88:91]
	v_mfma_f32_16x16x32_bf16 v[76:79], v[132:135], v[210:213], v[76:79]
	v_mfma_f32_16x16x32_bf16 v[72:75], v[140:143], v[210:213], v[72:75]
	s_setprio 0
	s_setprio 1
	v_mfma_f32_16x16x32_bf16 v[116:119], v[144:147], v[160:163], v[116:119]
	v_mfma_f32_16x16x32_bf16 v[112:115], v[152:155], v[160:163], v[112:115]
	v_mfma_f32_16x16x32_bf16 v[100:103], v[144:147], v[168:171], v[100:103]
	v_mfma_f32_16x16x32_bf16 v[96:99], v[152:155], v[168:171], v[96:99]
	v_mfma_f32_16x16x32_bf16 v[84:87], v[144:147], v[188:191], v[84:87]
	v_mfma_f32_16x16x32_bf16 v[80:83], v[152:155], v[188:191], v[80:83]
	v_mfma_f32_16x16x32_bf16 v[68:71], v[144:147], v[206:209], v[68:71]
	v_mfma_f32_16x16x32_bf16 v[64:67], v[152:155], v[206:209], v[64:67]
	v_mfma_f32_16x16x32_bf16 v[116:119], v[148:151], v[164:167], v[116:119]
	v_mfma_f32_16x16x32_bf16 v[112:115], v[156:159], v[164:167], v[112:115]
	v_mfma_f32_16x16x32_bf16 v[100:103], v[148:151], v[172:175], v[100:103]
	v_mfma_f32_16x16x32_bf16 v[96:99], v[156:159], v[172:175], v[96:99]
	v_mfma_f32_16x16x32_bf16 v[84:87], v[148:151], v[202:205], v[84:87]
	v_mfma_f32_16x16x32_bf16 v[80:83], v[156:159], v[202:205], v[80:83]
	v_mfma_f32_16x16x32_bf16 v[68:71], v[148:151], v[210:213], v[68:71]
	v_mfma_f32_16x16x32_bf16 v[64:67], v[156:159], v[210:213], v[64:67]
	s_setprio 0
	s_barrier
	s_add_u32 s34, s30, 0x8000
	s_addc_u32 s35, s31, 0
	s_add_i32 s50, s50, s3
	s_mov_b32 m0, s50
	s_nop 0
	global_load_lds_dwordx4 v176, s[34:35]
	s_add_i32 m0, s50, 0x2000
	s_add_u32 s30, s30, 0xc000
	s_addc_u32 s31, s31, 0
	global_load_lds_dwordx4 v178, s[34:35]
	s_add_i32 s34, s51, s3
	s_mov_b32 m0, s34
	s_nop 0
	global_load_lds_dwordx4 v176, s[30:31]
	s_add_i32 m0, s34, 0x2000
	s_nop 0
	global_load_lds_dwordx4 v178, s[30:31]
	s_mov_b32 m0, s42
	s_nop 0
	global_load_lds_dwordx4 v176, s[28:29]
	s_mov_b32 m0, s43
	s_nop 0
	global_load_lds_dwordx4 v178, s[28:29]
	ds_read_b128 v[160:163], v199 offset:49152
	ds_read_b128 v[164:167], v199 offset:50176
	ds_read_b128 v[168:171], v199 offset:51200
	ds_read_b128 v[172:175], v199 offset:52224
	ds_read_b128 v[188:191], v199 offset:53248
	ds_read_b128 v[202:205], v199 offset:54272
	ds_read_b128 v[206:209], v199 offset:55296
	ds_read_b128 v[210:213], v199 offset:56320
	s_waitcnt vmcnt(8)
	s_waitcnt lgkmcnt(0)
	s_barrier
	s_setprio 1
	s_waitcnt lgkmcnt(0)
	v_mfma_f32_16x16x32_bf16 v[60:63], v[128:131], v[160:163], v[60:63]
	v_mfma_f32_16x16x32_bf16 v[56:59], v[136:139], v[160:163], v[56:59]
	v_mfma_f32_16x16x32_bf16 v[44:47], v[128:131], v[168:171], v[44:47]
	v_mfma_f32_16x16x32_bf16 v[40:43], v[136:139], v[168:171], v[40:43]
	v_mfma_f32_16x16x32_bf16 v[28:31], v[128:131], v[188:191], v[28:31]
	v_mfma_f32_16x16x32_bf16 v[24:27], v[136:139], v[188:191], v[24:27]
	v_mfma_f32_16x16x32_bf16 v[12:15], v[128:131], v[206:209], v[12:15]
	v_mfma_f32_16x16x32_bf16 v[8:11], v[136:139], v[206:209], v[8:11]
	v_mfma_f32_16x16x32_bf16 v[60:63], v[132:135], v[164:167], v[60:63]
	v_mfma_f32_16x16x32_bf16 v[56:59], v[140:143], v[164:167], v[56:59]
	v_mfma_f32_16x16x32_bf16 v[44:47], v[132:135], v[172:175], v[44:47]
	v_mfma_f32_16x16x32_bf16 v[40:43], v[140:143], v[172:175], v[40:43]
	v_mfma_f32_16x16x32_bf16 v[28:31], v[132:135], v[202:205], v[28:31]
	v_mfma_f32_16x16x32_bf16 v[24:27], v[140:143], v[202:205], v[24:27]
	v_mfma_f32_16x16x32_bf16 v[12:15], v[132:135], v[210:213], v[12:15]
	v_mfma_f32_16x16x32_bf16 v[8:11], v[140:143], v[210:213], v[8:11]
	s_setprio 0
	s_setprio 1
	v_mfma_f32_16x16x32_bf16 v[52:55], v[144:147], v[160:163], v[52:55]
	v_mfma_f32_16x16x32_bf16 v[48:51], v[152:155], v[160:163], v[48:51]
	v_mfma_f32_16x16x32_bf16 v[36:39], v[144:147], v[168:171], v[36:39]
	v_mfma_f32_16x16x32_bf16 v[32:35], v[152:155], v[168:171], v[32:35]
	v_mfma_f32_16x16x32_bf16 v[20:23], v[144:147], v[188:191], v[20:23]
	v_mfma_f32_16x16x32_bf16 v[16:19], v[152:155], v[188:191], v[16:19]
	v_mfma_f32_16x16x32_bf16 v[4:7], v[144:147], v[206:209], v[4:7]
	v_mfma_f32_16x16x32_bf16 v[0:3], v[152:155], v[206:209], v[0:3]
	v_mfma_f32_16x16x32_bf16 v[52:55], v[148:151], v[164:167], v[52:55]
	v_mfma_f32_16x16x32_bf16 v[48:51], v[156:159], v[164:167], v[48:51]
	v_mfma_f32_16x16x32_bf16 v[36:39], v[148:151], v[172:175], v[36:39]
	v_mfma_f32_16x16x32_bf16 v[32:35], v[156:159], v[172:175], v[32:35]
	v_mfma_f32_16x16x32_bf16 v[20:23], v[148:151], v[202:205], v[20:23]
	v_mfma_f32_16x16x32_bf16 v[16:19], v[156:159], v[202:205], v[16:19]
	v_mfma_f32_16x16x32_bf16 v[4:7], v[148:151], v[210:213], v[4:7]
	v_mfma_f32_16x16x32_bf16 v[0:3], v[156:159], v[210:213], v[0:3]
	s_setprio 0
	s_barrier
	s_add_i32 s49, s49, 2
	s_add_u32 s26, s26, 0x10000
	s_addc_u32 s27, s27, 0
	s_add_u32 s25, s25, 0x10000
	s_addc_u32 s48, s48, 0
	s_cmp_gt_u32 s49, 61
	s_cbranch_scc0 .LBB0_469
	s_and_b64 vcc, exec, s[12:13]
	s_cbranch_vccz .LBB0_472
	s_barrier

.LBB0_640:
	ds_read_b128 v[56:59], v179
	ds_read_b128 v[60:63], v179 offset:1024
	ds_read_b128 v[64:67], v179 offset:2048
	ds_read_b128 v[68:71], v179 offset:3072
	ds_read_b128 v[144:147], v180
	ds_read_b128 v[148:151], v180 offset:1024
	ds_read_b128 v[152:155], v180 offset:2048
	ds_read_b128 v[156:159], v180 offset:3072
	s_add_u32 s22, s20, 0x4000
	s_addc_u32 s23, s21, 0
	s_cmp_eq_u32 s51, 60
	s_cselect_b32 s26, s19, s22
	s_cselect_b32 s27, s11, s23
	s_cselect_b32 s24, s48, s49
	s_cselect_b32 s25, s13, s50
	s_add_u32 s22, s26, 0x8000
	s_addc_u32 s23, s27, 0
	s_add_i32 m0, s30, 0xc000
	s_nop 0
	global_load_lds_dwordx4 v160, s[20:21]
	s_add_i32 m0, s30, 0xe000
	s_nop 0
	global_load_lds_dwordx4 v162, s[20:21]
	ds_read_b128 v[172:175], v181
	ds_read_b128 v[182:185], v181 offset:1024
	ds_read_b128 v[186:189], v181 offset:2048
	ds_read_b128 v[190:193], v181 offset:3072
	ds_read_b128 v[196:199], v181 offset:4096
	ds_read_b128 v[200:203], v181 offset:5120
	ds_read_b128 v[204:207], v181 offset:6144
	ds_read_b128 v[208:211], v181 offset:7168
	s_waitcnt vmcnt(8)
	s_waitcnt lgkmcnt(0)
	s_barrier
	s_setprio 1
	s_waitcnt lgkmcnt(0)
	v_mfma_f32_16x16x32_bf16 v[140:143], v[56:59], v[172:175], v[140:143]
	v_mfma_f32_16x16x32_bf16 v[136:139], v[64:67], v[172:175], v[136:139]
	v_mfma_f32_16x16x32_bf16 v[124:127], v[56:59], v[186:189], v[124:127]
	v_mfma_f32_16x16x32_bf16 v[120:123], v[64:67], v[186:189], v[120:123]
	v_mfma_f32_16x16x32_bf16 v[108:111], v[56:59], v[196:199], v[108:111]
	v_mfma_f32_16x16x32_bf16 v[104:107], v[64:67], v[196:199], v[104:107]
	v_mfma_f32_16x16x32_bf16 v[92:95], v[56:59], v[204:207], v[92:95]
	v_mfma_f32_16x16x32_bf16 v[88:91], v[64:67], v[204:207], v[88:91]
	v_mfma_f32_16x16x32_bf16 v[140:143], v[60:63], v[182:185], v[140:143]
	v_mfma_f32_16x16x32_bf16 v[136:139], v[68:71], v[182:185], v[136:139]
	v_mfma_f32_16x16x32_bf16 v[124:127], v[60:63], v[190:193], v[124:127]
	v_mfma_f32_16x16x32_bf16 v[120:123], v[68:71], v[190:193], v[120:123]
	v_mfma_f32_16x16x32_bf16 v[108:111], v[60:63], v[200:203], v[108:111]
	v_mfma_f32_16x16x32_bf16 v[104:107], v[68:71], v[200:203], v[104:107]
	v_mfma_f32_16x16x32_bf16 v[92:95], v[60:63], v[208:211], v[92:95]
	v_mfma_f32_16x16x32_bf16 v[88:91], v[68:71], v[208:211], v[88:91]
	s_setprio 0
	s_setprio 1
	v_mfma_f32_16x16x32_bf16 v[132:135], v[144:147], v[172:175], v[132:135]
	v_mfma_f32_16x16x32_bf16 v[128:131], v[152:155], v[172:175], v[128:131]
	v_mfma_f32_16x16x32_bf16 v[116:119], v[144:147], v[186:189], v[116:119]
	v_mfma_f32_16x16x32_bf16 v[112:115], v[152:155], v[186:189], v[112:115]
	v_mfma_f32_16x16x32_bf16 v[100:103], v[144:147], v[196:199], v[100:103]
	v_mfma_f32_16x16x32_bf16 v[96:99], v[152:155], v[196:199], v[96:99]
	v_mfma_f32_16x16x32_bf16 v[84:87], v[144:147], v[204:207], v[84:87]
	v_mfma_f32_16x16x32_bf16 v[80:83], v[152:155], v[204:207], v[80:83]
	v_mfma_f32_16x16x32_bf16 v[132:135], v[148:151], v[182:185], v[132:135]
	v_mfma_f32_16x16x32_bf16 v[128:131], v[156:159], v[182:185], v[128:131]
	v_mfma_f32_16x16x32_bf16 v[116:119], v[148:151], v[190:193], v[116:119]
	v_mfma_f32_16x16x32_bf16 v[112:115], v[156:159], v[190:193], v[112:115]
	v_mfma_f32_16x16x32_bf16 v[100:103], v[148:151], v[200:203], v[100:103]
	v_mfma_f32_16x16x32_bf16 v[96:99], v[156:159], v[200:203], v[96:99]
	v_mfma_f32_16x16x32_bf16 v[84:87], v[148:151], v[208:211], v[84:87]
	v_mfma_f32_16x16x32_bf16 v[80:83], v[156:159], v[208:211], v[80:83]
	s_setprio 0
	s_barrier
	s_add_i32 s52, s46, s3
	s_mov_b32 m0, s52
	s_nop 0
	global_load_lds_dwordx4 v160, s[24:25]
	s_add_i32 m0, s52, 0x2000
	s_add_u32 s52, s24, 0x4000
	s_addc_u32 s53, s25, 0
	s_add_i32 s54, s47, s3
	global_load_lds_dwordx4 v162, s[24:25]
	s_mov_b32 m0, s54
	s_nop 0
	global_load_lds_dwordx4 v160, s[52:53]
	s_add_i32 m0, s54, 0x2000
	s_nop 0
	global_load_lds_dwordx4 v162, s[52:53]
	s_mov_b32 m0, s30
	s_nop 0
	global_load_lds_dwordx4 v160, s[26:27]
	s_mov_b32 m0, s31
	s_nop 0
	global_load_lds_dwordx4 v162, s[26:27]
	ds_read_b128 v[172:175], v181 offset:16384
	ds_read_b128 v[182:185], v181 offset:17408
	ds_read_b128 v[186:189], v181 offset:18432
	ds_read_b128 v[190:193], v181 offset:19456
	ds_read_b128 v[196:199], v181 offset:20480
	ds_read_b128 v[200:203], v181 offset:21504
	ds_read_b128 v[204:207], v181 offset:22528
	ds_read_b128 v[208:211], v181 offset:23552
	s_waitcnt vmcnt(8)
	s_waitcnt lgkmcnt(0)
	s_barrier
	s_setprio 1
	s_waitcnt lgkmcnt(0)
	v_mfma_f32_16x16x32_bf16 v[76:79], v[56:59], v[172:175], v[76:79]
	v_mfma_f32_16x16x32_bf16 v[72:75], v[64:67], v[172:175], v[72:75]
	v_mfma_f32_16x16x32_bf16 v[44:47], v[56:59], v[186:189], v[44:47]
	v_mfma_f32_16x16x32_bf16 v[40:43], v[64:67], v[186:189], v[40:43]
	v_mfma_f32_16x16x32_bf16 v[28:31], v[56:59], v[196:199], v[28:31]
	v_mfma_f32_16x16x32_bf16 v[24:27], v[64:67], v[196:199], v[24:27]
	v_mfma_f32_16x16x32_bf16 v[12:15], v[56:59], v[204:207], v[12:15]
	v_mfma_f32_16x16x32_bf16 v[8:11], v[64:67], v[204:207], v[8:11]
	v_mfma_f32_16x16x32_bf16 v[76:79], v[60:63], v[182:185], v[76:79]
	v_mfma_f32_16x16x32_bf16 v[72:75], v[68:71], v[182:185], v[72:75]
	v_mfma_f32_16x16x32_bf16 v[44:47], v[60:63], v[190:193], v[44:47]
	v_mfma_f32_16x16x32_bf16 v[40:43], v[68:71], v[190:193], v[40:43]
	v_mfma_f32_16x16x32_bf16 v[28:31], v[60:63], v[200:203], v[28:31]
	v_mfma_f32_16x16x32_bf16 v[24:27], v[68:71], v[200:203], v[24:27]
	v_mfma_f32_16x16x32_bf16 v[12:15], v[60:63], v[208:211], v[12:15]
	v_mfma_f32_16x16x32_bf16 v[8:11], v[68:71], v[208:211], v[8:11]
	s_setprio 0
	s_setprio 1
	v_mfma_f32_16x16x32_bf16 v[52:55], v[144:147], v[172:175], v[52:55]
	v_mfma_f32_16x16x32_bf16 v[48:51], v[152:155], v[172:175], v[48:51]
	v_mfma_f32_16x16x32_bf16 v[36:39], v[144:147], v[186:189], v[36:39]
	v_mfma_f32_16x16x32_bf16 v[32:35], v[152:155], v[186:189], v[32:35]
	v_mfma_f32_16x16x32_bf16 v[20:23], v[144:147], v[196:199], v[20:23]
	v_mfma_f32_16x16x32_bf16 v[16:19], v[152:155], v[196:199], v[16:19]
	v_mfma_f32_16x16x32_bf16 v[4:7], v[144:147], v[204:207], v[4:7]
	v_mfma_f32_16x16x32_bf16 v[0:3], v[152:155], v[204:207], v[0:3]
	v_mfma_f32_16x16x32_bf16 v[52:55], v[148:151], v[182:185], v[52:55]
	v_mfma_f32_16x16x32_bf16 v[48:51], v[156:159], v[182:185], v[48:51]
	v_mfma_f32_16x16x32_bf16 v[36:39], v[148:151], v[190:193], v[36:39]
	v_mfma_f32_16x16x32_bf16 v[32:35], v[156:159], v[190:193], v[32:35]
	v_mfma_f32_16x16x32_bf16 v[20:23], v[148:151], v[200:203], v[20:23]
	v_mfma_f32_16x16x32_bf16 v[16:19], v[156:159], v[200:203], v[16:19]
	v_mfma_f32_16x16x32_bf16 v[4:7], v[148:151], v[208:211], v[4:7]
	v_mfma_f32_16x16x32_bf16 v[0:3], v[156:159], v[208:211], v[0:3]
	s_setprio 0
	s_barrier
	s_add_i32 s52, 0, 0x18000
	s_add_i32 s53, 0, 0x1c000
	v_add_u32_e32 v68, s52, v178
	v_add_u32_e32 v156, s53, v178
	ds_read_b128 v[56:59], v68
	ds_read_b128 v[60:63], v68 offset:1024
	ds_read_b128 v[64:67], v68 offset:2048
	ds_read_b128 v[68:71], v68 offset:3072
	ds_read_b128 v[144:147], v156
	ds_read_b128 v[148:151], v156 offset:1024
	ds_read_b128 v[152:155], v156 offset:2048
	ds_read_b128 v[156:159], v156 offset:3072
	s_add_u32 s26, s26, 0x4000
	s_addc_u32 s27, s27, 0
	s_mov_b32 m0, s33
	s_nop 0
	global_load_lds_dwordx4 v160, s[26:27]
	s_mov_b32 m0, s34
	s_nop 0
	global_load_lds_dwordx4 v162, s[26:27]
	ds_read_b128 v[172:175], v181 offset:32768
	ds_read_b128 v[182:185], v181 offset:33792
	ds_read_b128 v[186:189], v181 offset:34816
	ds_read_b128 v[190:193], v181 offset:35840
	ds_read_b128 v[196:199], v181 offset:36864
	ds_read_b128 v[200:203], v181 offset:37888
	ds_read_b128 v[204:207], v181 offset:38912
	ds_read_b128 v[208:211], v181 offset:39936
	s_waitcnt vmcnt(8)
	s_waitcnt lgkmcnt(0)
	s_barrier
	s_setprio 1
	s_waitcnt lgkmcnt(0)
	v_mfma_f32_16x16x32_bf16 v[140:143], v[56:59], v[172:175], v[140:143]
	v_mfma_f32_16x16x32_bf16 v[136:139], v[64:67], v[172:175], v[136:139]
	v_mfma_f32_16x16x32_bf16 v[124:127], v[56:59], v[186:189], v[124:127]
	v_mfma_f32_16x16x32_bf16 v[120:123], v[64:67], v[186:189], v[120:123]
	v_mfma_f32_16x16x32_bf16 v[108:111], v[56:59], v[196:199], v[108:111]
	v_mfma_f32_16x16x32_bf16 v[104:107], v[64:67], v[196:199], v[104:107]
	v_mfma_f32_16x16x32_bf16 v[92:95], v[56:59], v[204:207], v[92:95]
	v_mfma_f32_16x16x32_bf16 v[88:91], v[64:67], v[204:207], v[88:91]
	v_mfma_f32_16x16x32_bf16 v[140:143], v[60:63], v[182:185], v[140:143]
	v_mfma_f32_16x16x32_bf16 v[136:139], v[68:71], v[182:185], v[136:139]
	v_mfma_f32_16x16x32_bf16 v[124:127], v[60:63], v[190:193], v[124:127]
	v_mfma_f32_16x16x32_bf16 v[120:123], v[68:71], v[190:193], v[120:123]
	v_mfma_f32_16x16x32_bf16 v[108:111], v[60:63], v[200:203], v[108:111]
	v_mfma_f32_16x16x32_bf16 v[104:107], v[68:71], v[200:203], v[104:107]
	v_mfma_f32_16x16x32_bf16 v[92:95], v[60:63], v[208:211], v[92:95]
	v_mfma_f32_16x16x32_bf16 v[88:91], v[68:71], v[208:211], v[88:91]
	s_setprio 0
	s_setprio 1
	v_mfma_f32_16x16x32_bf16 v[132:135], v[144:147], v[172:175], v[132:135]
	v_mfma_f32_16x16x32_bf16 v[128:131], v[152:155], v[172:175], v[128:131]
	v_mfma_f32_16x16x32_bf16 v[116:119], v[144:147], v[186:189], v[116:119]
	v_mfma_f32_16x16x32_bf16 v[112:115], v[152:155], v[186:189], v[112:115]
	v_mfma_f32_16x16x32_bf16 v[100:103], v[144:147], v[196:199], v[100:103]
	v_mfma_f32_16x16x32_bf16 v[96:99], v[152:155], v[196:199], v[96:99]
	v_mfma_f32_16x16x32_bf16 v[84:87], v[144:147], v[204:207], v[84:87]
	v_mfma_f32_16x16x32_bf16 v[80:83], v[152:155], v[204:207], v[80:83]
	v_mfma_f32_16x16x32_bf16 v[132:135], v[148:151], v[182:185], v[132:135]
	v_mfma_f32_16x16x32_bf16 v[128:131], v[156:159], v[182:185], v[128:131]
	v_mfma_f32_16x16x32_bf16 v[116:119], v[148:151], v[190:193], v[116:119]
	v_mfma_f32_16x16x32_bf16 v[112:115], v[156:159], v[190:193], v[112:115]
	v_mfma_f32_16x16x32_bf16 v[100:103], v[148:151], v[200:203], v[100:103]
	v_mfma_f32_16x16x32_bf16 v[96:99], v[156:159], v[200:203], v[96:99]
	v_mfma_f32_16x16x32_bf16 v[84:87], v[148:151], v[208:211], v[84:87]
	v_mfma_f32_16x16x32_bf16 v[80:83], v[156:159], v[208:211], v[80:83]
	s_setprio 0
	s_barrier
	s_add_u32 s26, s24, 0x8000
	s_addc_u32 s27, s25, 0
	s_add_i32 s52, s52, s3
	s_mov_b32 m0, s52
	s_nop 0
	global_load_lds_dwordx4 v160, s[26:27]
	s_add_i32 m0, s52, 0x2000
	s_add_u32 s24, s24, 0xc000
	s_addc_u32 s25, s25, 0
	global_load_lds_dwordx4 v162, s[26:27]
	s_add_i32 s26, s53, s3
	s_mov_b32 m0, s26
	s_nop 0
	global_load_lds_dwordx4 v160, s[24:25]
	s_add_i32 m0, s26, 0x2000
	s_nop 0
	global_load_lds_dwordx4 v162, s[24:25]
	s_mov_b32 m0, s39
	s_nop 0
	global_load_lds_dwordx4 v160, s[22:23]
	s_mov_b32 m0, s40
	s_nop 0
	global_load_lds_dwordx4 v162, s[22:23]
	ds_read_b128 v[172:175], v181 offset:49152
	ds_read_b128 v[182:185], v181 offset:50176
	ds_read_b128 v[186:189], v181 offset:51200
	ds_read_b128 v[190:193], v181 offset:52224
	ds_read_b128 v[196:199], v181 offset:53248
	ds_read_b128 v[200:203], v181 offset:54272
	ds_read_b128 v[204:207], v181 offset:55296
	ds_read_b128 v[208:211], v181 offset:56320
	s_waitcnt vmcnt(8)
	s_waitcnt lgkmcnt(0)
	s_barrier
	s_setprio 1
	s_waitcnt lgkmcnt(0)
	v_mfma_f32_16x16x32_bf16 v[76:79], v[56:59], v[172:175], v[76:79]
	v_mfma_f32_16x16x32_bf16 v[72:75], v[64:67], v[172:175], v[72:75]
	v_mfma_f32_16x16x32_bf16 v[44:47], v[56:59], v[186:189], v[44:47]
	v_mfma_f32_16x16x32_bf16 v[40:43], v[64:67], v[186:189], v[40:43]
	v_mfma_f32_16x16x32_bf16 v[28:31], v[56:59], v[196:199], v[28:31]
	v_mfma_f32_16x16x32_bf16 v[24:27], v[64:67], v[196:199], v[24:27]
	v_mfma_f32_16x16x32_bf16 v[12:15], v[56:59], v[204:207], v[12:15]
	v_mfma_f32_16x16x32_bf16 v[8:11], v[64:67], v[204:207], v[8:11]
	v_mfma_f32_16x16x32_bf16 v[76:79], v[60:63], v[182:185], v[76:79]
	v_mfma_f32_16x16x32_bf16 v[72:75], v[68:71], v[182:185], v[72:75]
	v_mfma_f32_16x16x32_bf16 v[44:47], v[60:63], v[190:193], v[44:47]
	v_mfma_f32_16x16x32_bf16 v[40:43], v[68:71], v[190:193], v[40:43]
	v_mfma_f32_16x16x32_bf16 v[28:31], v[60:63], v[200:203], v[28:31]
	v_mfma_f32_16x16x32_bf16 v[24:27], v[68:71], v[200:203], v[24:27]
	v_mfma_f32_16x16x32_bf16 v[12:15], v[60:63], v[208:211], v[12:15]
	v_mfma_f32_16x16x32_bf16 v[8:11], v[68:71], v[208:211], v[8:11]
	s_setprio 0
	s_setprio 1
	v_mfma_f32_16x16x32_bf16 v[52:55], v[144:147], v[172:175], v[52:55]
	v_mfma_f32_16x16x32_bf16 v[48:51], v[152:155], v[172:175], v[48:51]
	v_mfma_f32_16x16x32_bf16 v[36:39], v[144:147], v[186:189], v[36:39]
	v_mfma_f32_16x16x32_bf16 v[32:35], v[152:155], v[186:189], v[32:35]
	v_mfma_f32_16x16x32_bf16 v[20:23], v[144:147], v[196:199], v[20:23]
	v_mfma_f32_16x16x32_bf16 v[16:19], v[152:155], v[196:199], v[16:19]
	v_mfma_f32_16x16x32_bf16 v[4:7], v[144:147], v[204:207], v[4:7]
	v_mfma_f32_16x16x32_bf16 v[0:3], v[152:155], v[204:207], v[0:3]
	v_mfma_f32_16x16x32_bf16 v[52:55], v[148:151], v[182:185], v[52:55]
	v_mfma_f32_16x16x32_bf16 v[48:51], v[156:159], v[182:185], v[48:51]
	v_mfma_f32_16x16x32_bf16 v[36:39], v[148:151], v[190:193], v[36:39]
	v_mfma_f32_16x16x32_bf16 v[32:35], v[156:159], v[190:193], v[32:35]
	v_mfma_f32_16x16x32_bf16 v[20:23], v[148:151], v[200:203], v[20:23]
	v_mfma_f32_16x16x32_bf16 v[16:19], v[156:159], v[200:203], v[16:19]
	v_mfma_f32_16x16x32_bf16 v[4:7], v[148:151], v[208:211], v[4:7]
	v_mfma_f32_16x16x32_bf16 v[0:3], v[156:159], v[208:211], v[0:3]
	s_setprio 0
	s_barrier
	s_add_i32 s51, s51, 2
	s_add_u32 s20, s20, 0x10000
	s_addc_u32 s21, s21, 0
	s_add_u32 s49, s49, 0x10000
	s_addc_u32 s50, s50, 0
	s_cmp_gt_u32 s51, 61
	s_cbranch_scc0 .LBB0_640
	s_and_b64 vcc, exec, s[6:7]
	s_cbranch_vccz .LBB0_643
	s_barrier

.LBB0_716:
	ds_read_b128 v[138:141], v145
	ds_read_b128 v[148:151], v145 offset:1024
	ds_read_b128 v[152:155], v145 offset:2048
	ds_read_b128 v[156:159], v145 offset:3072
	ds_read_b128 v[160:163], v146
	ds_read_b128 v[164:167], v146 offset:1024
	ds_read_b128 v[168:171], v146 offset:2048
	ds_read_b128 v[172:175], v146 offset:3072
	s_add_u32 s20, s18, 0x4000
	s_addc_u32 s21, s19, 0
	s_cmp_eq_u32 s48, 60
	s_cselect_b32 s24, s44, s20
	s_cselect_b32 s25, s9, s21
	s_cselect_b32 s22, s45, s46
	s_cselect_b32 s23, s11, s47
	s_add_u32 s20, s24, 0x8000
	s_addc_u32 s21, s25, 0
	s_add_i32 m0, s28, 0xc000
	s_nop 0
	global_load_lds_dwordx4 v128, s[18:19]
	s_add_i32 m0, s28, 0xe000
	s_nop 0
	global_load_lds_dwordx4 v130, s[18:19]
	ds_read_b128 v[176:179], v147
	ds_read_b128 v[180:183], v147 offset:1024
	ds_read_b128 v[184:187], v147 offset:2048
	ds_read_b128 v[188:191], v147 offset:3072
	ds_read_b128 v[192:195], v147 offset:4096
	ds_read_b128 v[196:199], v147 offset:5120
	ds_read_b128 v[200:203], v147 offset:6144
	ds_read_b128 v[204:207], v147 offset:7168
	s_waitcnt vmcnt(8)
	s_waitcnt lgkmcnt(0)
	s_barrier
	s_setprio 1
	s_waitcnt lgkmcnt(0)
	v_mfma_f32_16x16x32_bf16 v[124:127], v[138:141], v[176:179], v[124:127]
	v_mfma_f32_16x16x32_bf16 v[120:123], v[152:155], v[176:179], v[120:123]
	v_mfma_f32_16x16x32_bf16 v[116:119], v[138:141], v[184:187], v[116:119]
	v_mfma_f32_16x16x32_bf16 v[104:107], v[152:155], v[184:187], v[104:107]
	v_mfma_f32_16x16x32_bf16 v[92:95], v[138:141], v[192:195], v[92:95]
	v_mfma_f32_16x16x32_bf16 v[88:91], v[152:155], v[192:195], v[88:91]
	v_mfma_f32_16x16x32_bf16 v[84:87], v[138:141], v[200:203], v[84:87]
	v_mfma_f32_16x16x32_bf16 v[72:75], v[152:155], v[200:203], v[72:75]
	v_mfma_f32_16x16x32_bf16 v[124:127], v[148:151], v[180:183], v[124:127]
	v_mfma_f32_16x16x32_bf16 v[120:123], v[156:159], v[180:183], v[120:123]
	v_mfma_f32_16x16x32_bf16 v[116:119], v[148:151], v[188:191], v[116:119]
	v_mfma_f32_16x16x32_bf16 v[104:107], v[156:159], v[188:191], v[104:107]
	v_mfma_f32_16x16x32_bf16 v[92:95], v[148:151], v[196:199], v[92:95]
	v_mfma_f32_16x16x32_bf16 v[88:91], v[156:159], v[196:199], v[88:91]
	v_mfma_f32_16x16x32_bf16 v[84:87], v[148:151], v[204:207], v[84:87]
	v_mfma_f32_16x16x32_bf16 v[72:75], v[156:159], v[204:207], v[72:75]
	s_setprio 0
	s_setprio 1
	v_mfma_f32_16x16x32_bf16 v[112:115], v[160:163], v[176:179], v[112:115]
	v_mfma_f32_16x16x32_bf16 v[108:111], v[168:171], v[176:179], v[108:111]
	v_mfma_f32_16x16x32_bf16 v[100:103], v[160:163], v[184:187], v[100:103]
	v_mfma_f32_16x16x32_bf16 v[96:99], v[168:171], v[184:187], v[96:99]
	v_mfma_f32_16x16x32_bf16 v[80:83], v[160:163], v[192:195], v[80:83]
	v_mfma_f32_16x16x32_bf16 v[76:79], v[168:171], v[192:195], v[76:79]
	v_mfma_f32_16x16x32_bf16 v[68:71], v[160:163], v[200:203], v[68:71]
	v_mfma_f32_16x16x32_bf16 v[64:67], v[168:171], v[200:203], v[64:67]
	v_mfma_f32_16x16x32_bf16 v[112:115], v[164:167], v[180:183], v[112:115]
	v_mfma_f32_16x16x32_bf16 v[108:111], v[172:175], v[180:183], v[108:111]
	v_mfma_f32_16x16x32_bf16 v[100:103], v[164:167], v[188:191], v[100:103]
	v_mfma_f32_16x16x32_bf16 v[96:99], v[172:175], v[188:191], v[96:99]
	v_mfma_f32_16x16x32_bf16 v[80:83], v[164:167], v[196:199], v[80:83]
	v_mfma_f32_16x16x32_bf16 v[76:79], v[172:175], v[196:199], v[76:79]
	v_mfma_f32_16x16x32_bf16 v[68:71], v[164:167], v[204:207], v[68:71]
	v_mfma_f32_16x16x32_bf16 v[64:67], v[172:175], v[204:207], v[64:67]
	s_setprio 0
	s_barrier
	s_add_i32 s49, s42, s3
	s_mov_b32 m0, s49
	s_nop 0
	global_load_lds_dwordx4 v128, s[22:23]
	s_add_i32 m0, s49, 0x2000
	s_add_u32 s50, s22, 0x4000
	s_addc_u32 s51, s23, 0
	s_add_i32 s49, s43, s3
	global_load_lds_dwordx4 v130, s[22:23]
	s_mov_b32 m0, s49
	s_nop 0
	global_load_lds_dwordx4 v128, s[50:51]
	s_add_i32 m0, s49, 0x2000
	s_nop 0
	global_load_lds_dwordx4 v130, s[50:51]
	s_mov_b32 m0, s28
	s_nop 0
	global_load_lds_dwordx4 v128, s[24:25]
	s_mov_b32 m0, s29
	s_nop 0
	global_load_lds_dwordx4 v130, s[24:25]
	ds_read_b128 v[176:179], v147 offset:16384
	ds_read_b128 v[180:183], v147 offset:17408
	ds_read_b128 v[184:187], v147 offset:18432
	ds_read_b128 v[188:191], v147 offset:19456
	ds_read_b128 v[192:195], v147 offset:20480
	ds_read_b128 v[196:199], v147 offset:21504
	ds_read_b128 v[200:203], v147 offset:22528
	ds_read_b128 v[204:207], v147 offset:23552
	s_waitcnt vmcnt(8)
	s_waitcnt lgkmcnt(0)
	s_barrier
	s_setprio 1
	s_waitcnt lgkmcnt(0)
	v_mfma_f32_16x16x32_bf16 v[60:63], v[138:141], v[176:179], v[60:63]
	v_mfma_f32_16x16x32_bf16 v[56:59], v[152:155], v[176:179], v[56:59]
	v_mfma_f32_16x16x32_bf16 v[48:51], v[138:141], v[184:187], v[48:51]
	v_mfma_f32_16x16x32_bf16 v[40:43], v[152:155], v[184:187], v[40:43]
	v_mfma_f32_16x16x32_bf16 v[28:31], v[138:141], v[192:195], v[28:31]
	v_mfma_f32_16x16x32_bf16 v[24:27], v[152:155], v[192:195], v[24:27]
	v_mfma_f32_16x16x32_bf16 v[16:19], v[138:141], v[200:203], v[16:19]
	v_mfma_f32_16x16x32_bf16 v[8:11], v[152:155], v[200:203], v[8:11]
	v_mfma_f32_16x16x32_bf16 v[60:63], v[148:151], v[180:183], v[60:63]
	v_mfma_f32_16x16x32_bf16 v[56:59], v[156:159], v[180:183], v[56:59]
	v_mfma_f32_16x16x32_bf16 v[48:51], v[148:151], v[188:191], v[48:51]
	v_mfma_f32_16x16x32_bf16 v[40:43], v[156:159], v[188:191], v[40:43]
	v_mfma_f32_16x16x32_bf16 v[28:31], v[148:151], v[196:199], v[28:31]
	v_mfma_f32_16x16x32_bf16 v[24:27], v[156:159], v[196:199], v[24:27]
	v_mfma_f32_16x16x32_bf16 v[16:19], v[148:151], v[204:207], v[16:19]
	v_mfma_f32_16x16x32_bf16 v[8:11], v[156:159], v[204:207], v[8:11]
	s_setprio 0
	s_setprio 1
	v_mfma_f32_16x16x32_bf16 v[52:55], v[160:163], v[176:179], v[52:55]
	v_mfma_f32_16x16x32_bf16 v[44:47], v[168:171], v[176:179], v[44:47]
	v_mfma_f32_16x16x32_bf16 v[36:39], v[160:163], v[184:187], v[36:39]
	v_mfma_f32_16x16x32_bf16 v[32:35], v[168:171], v[184:187], v[32:35]
	v_mfma_f32_16x16x32_bf16 v[20:23], v[160:163], v[192:195], v[20:23]
	v_mfma_f32_16x16x32_bf16 v[12:15], v[168:171], v[192:195], v[12:15]
	v_mfma_f32_16x16x32_bf16 v[4:7], v[160:163], v[200:203], v[4:7]
	v_mfma_f32_16x16x32_bf16 v[0:3], v[168:171], v[200:203], v[0:3]
	v_mfma_f32_16x16x32_bf16 v[52:55], v[164:167], v[180:183], v[52:55]
	v_mfma_f32_16x16x32_bf16 v[44:47], v[172:175], v[180:183], v[44:47]
	v_mfma_f32_16x16x32_bf16 v[36:39], v[164:167], v[188:191], v[36:39]
	v_mfma_f32_16x16x32_bf16 v[32:35], v[172:175], v[188:191], v[32:35]
	v_mfma_f32_16x16x32_bf16 v[20:23], v[164:167], v[196:199], v[20:23]
	v_mfma_f32_16x16x32_bf16 v[12:15], v[172:175], v[196:199], v[12:15]
	v_mfma_f32_16x16x32_bf16 v[4:7], v[164:167], v[204:207], v[4:7]
	v_mfma_f32_16x16x32_bf16 v[0:3], v[172:175], v[204:207], v[0:3]
	s_setprio 0
	s_barrier
	s_add_i32 s49, 0, 0x18000
	v_add_u32_e32 v132, s49, v144
	s_add_i32 s50, 0, 0x1c000
	ds_read_b128 v[138:141], v132
	ds_read_b128 v[148:151], v132 offset:1024
	ds_read_b128 v[152:155], v132 offset:2048
	ds_read_b128 v[156:159], v132 offset:3072
	v_add_u32_e32 v132, s50, v144
	ds_read_b128 v[160:163], v132
	ds_read_b128 v[164:167], v132 offset:1024
	ds_read_b128 v[168:171], v132 offset:2048
	ds_read_b128 v[172:175], v132 offset:3072
	s_add_u32 s24, s24, 0x4000
	s_addc_u32 s25, s25, 0
	s_mov_b32 m0, s30
	s_nop 0
	global_load_lds_dwordx4 v128, s[24:25]
	s_mov_b32 m0, s31
	s_nop 0
	global_load_lds_dwordx4 v130, s[24:25]
	ds_read_b128 v[176:179], v147 offset:32768
	ds_read_b128 v[180:183], v147 offset:33792
	ds_read_b128 v[184:187], v147 offset:34816
	ds_read_b128 v[188:191], v147 offset:35840
	ds_read_b128 v[192:195], v147 offset:36864
	ds_read_b128 v[196:199], v147 offset:37888
	ds_read_b128 v[200:203], v147 offset:38912
	ds_read_b128 v[204:207], v147 offset:39936
	s_waitcnt vmcnt(8)
	s_waitcnt lgkmcnt(0)
	s_barrier
	s_setprio 1
	s_waitcnt lgkmcnt(0)
	v_mfma_f32_16x16x32_bf16 v[124:127], v[138:141], v[176:179], v[124:127]
	v_mfma_f32_16x16x32_bf16 v[120:123], v[152:155], v[176:179], v[120:123]
	v_mfma_f32_16x16x32_bf16 v[116:119], v[138:141], v[184:187], v[116:119]
	v_mfma_f32_16x16x32_bf16 v[104:107], v[152:155], v[184:187], v[104:107]
	v_mfma_f32_16x16x32_bf16 v[92:95], v[138:141], v[192:195], v[92:95]
	v_mfma_f32_16x16x32_bf16 v[88:91], v[152:155], v[192:195], v[88:91]
	v_mfma_f32_16x16x32_bf16 v[84:87], v[138:141], v[200:203], v[84:87]
	v_mfma_f32_16x16x32_bf16 v[72:75], v[152:155], v[200:203], v[72:75]
	v_mfma_f32_16x16x32_bf16 v[124:127], v[148:151], v[180:183], v[124:127]
	v_mfma_f32_16x16x32_bf16 v[120:123], v[156:159], v[180:183], v[120:123]
	v_mfma_f32_16x16x32_bf16 v[116:119], v[148:151], v[188:191], v[116:119]
	v_mfma_f32_16x16x32_bf16 v[104:107], v[156:159], v[188:191], v[104:107]
	v_mfma_f32_16x16x32_bf16 v[92:95], v[148:151], v[196:199], v[92:95]
	v_mfma_f32_16x16x32_bf16 v[88:91], v[156:159], v[196:199], v[88:91]
	v_mfma_f32_16x16x32_bf16 v[84:87], v[148:151], v[204:207], v[84:87]
	v_mfma_f32_16x16x32_bf16 v[72:75], v[156:159], v[204:207], v[72:75]
	s_setprio 0
	s_setprio 1
	v_mfma_f32_16x16x32_bf16 v[112:115], v[160:163], v[176:179], v[112:115]
	v_mfma_f32_16x16x32_bf16 v[108:111], v[168:171], v[176:179], v[108:111]
	v_mfma_f32_16x16x32_bf16 v[100:103], v[160:163], v[184:187], v[100:103]
	v_mfma_f32_16x16x32_bf16 v[96:99], v[168:171], v[184:187], v[96:99]
	v_mfma_f32_16x16x32_bf16 v[80:83], v[160:163], v[192:195], v[80:83]
	v_mfma_f32_16x16x32_bf16 v[76:79], v[168:171], v[192:195], v[76:79]
	v_mfma_f32_16x16x32_bf16 v[68:71], v[160:163], v[200:203], v[68:71]
	v_mfma_f32_16x16x32_bf16 v[64:67], v[168:171], v[200:203], v[64:67]
	v_mfma_f32_16x16x32_bf16 v[112:115], v[164:167], v[180:183], v[112:115]
	v_mfma_f32_16x16x32_bf16 v[108:111], v[172:175], v[180:183], v[108:111]
	v_mfma_f32_16x16x32_bf16 v[100:103], v[164:167], v[188:191], v[100:103]
	v_mfma_f32_16x16x32_bf16 v[96:99], v[172:175], v[188:191], v[96:99]
	v_mfma_f32_16x16x32_bf16 v[80:83], v[164:167], v[196:199], v[80:83]
	v_mfma_f32_16x16x32_bf16 v[76:79], v[172:175], v[196:199], v[76:79]
	v_mfma_f32_16x16x32_bf16 v[68:71], v[164:167], v[204:207], v[68:71]
	v_mfma_f32_16x16x32_bf16 v[64:67], v[172:175], v[204:207], v[64:67]
	s_setprio 0
	s_barrier
	s_add_u32 s24, s22, 0x8000
	s_addc_u32 s25, s23, 0
	s_add_i32 s49, s49, s3
	s_mov_b32 m0, s49
	s_nop 0
	global_load_lds_dwordx4 v128, s[24:25]
	s_add_i32 m0, s49, 0x2000
	s_add_u32 s22, s22, 0xc000
	s_addc_u32 s23, s23, 0
	global_load_lds_dwordx4 v130, s[24:25]
	s_add_i32 s24, s50, s3
	s_mov_b32 m0, s24
	s_nop 0
	global_load_lds_dwordx4 v128, s[22:23]
	s_add_i32 m0, s24, 0x2000
	s_nop 0
	global_load_lds_dwordx4 v130, s[22:23]
	s_mov_b32 m0, s36
	s_nop 0
	global_load_lds_dwordx4 v128, s[20:21]
	s_mov_b32 m0, s37
	s_nop 0
	global_load_lds_dwordx4 v130, s[20:21]
	ds_read_b128 v[176:179], v147 offset:49152
	ds_read_b128 v[180:183], v147 offset:50176
	ds_read_b128 v[184:187], v147 offset:51200
	ds_read_b128 v[188:191], v147 offset:52224
	ds_read_b128 v[192:195], v147 offset:53248
	ds_read_b128 v[196:199], v147 offset:54272
	ds_read_b128 v[200:203], v147 offset:55296
	ds_read_b128 v[204:207], v147 offset:56320
	s_waitcnt vmcnt(8)
	s_waitcnt lgkmcnt(0)
	s_barrier
	s_setprio 1
	s_waitcnt lgkmcnt(0)
	v_mfma_f32_16x16x32_bf16 v[60:63], v[138:141], v[176:179], v[60:63]
	v_mfma_f32_16x16x32_bf16 v[56:59], v[152:155], v[176:179], v[56:59]
	v_mfma_f32_16x16x32_bf16 v[48:51], v[138:141], v[184:187], v[48:51]
	v_mfma_f32_16x16x32_bf16 v[40:43], v[152:155], v[184:187], v[40:43]
	v_mfma_f32_16x16x32_bf16 v[28:31], v[138:141], v[192:195], v[28:31]
	v_mfma_f32_16x16x32_bf16 v[24:27], v[152:155], v[192:195], v[24:27]
	v_mfma_f32_16x16x32_bf16 v[16:19], v[138:141], v[200:203], v[16:19]
	v_mfma_f32_16x16x32_bf16 v[8:11], v[152:155], v[200:203], v[8:11]
	v_mfma_f32_16x16x32_bf16 v[60:63], v[148:151], v[180:183], v[60:63]
	v_mfma_f32_16x16x32_bf16 v[56:59], v[156:159], v[180:183], v[56:59]
	v_mfma_f32_16x16x32_bf16 v[48:51], v[148:151], v[188:191], v[48:51]
	v_mfma_f32_16x16x32_bf16 v[40:43], v[156:159], v[188:191], v[40:43]
	v_mfma_f32_16x16x32_bf16 v[28:31], v[148:151], v[196:199], v[28:31]
	v_mfma_f32_16x16x32_bf16 v[24:27], v[156:159], v[196:199], v[24:27]
	v_mfma_f32_16x16x32_bf16 v[16:19], v[148:151], v[204:207], v[16:19]
	v_mfma_f32_16x16x32_bf16 v[8:11], v[156:159], v[204:207], v[8:11]
	s_setprio 0
	s_setprio 1
	v_mfma_f32_16x16x32_bf16 v[52:55], v[160:163], v[176:179], v[52:55]
	v_mfma_f32_16x16x32_bf16 v[44:47], v[168:171], v[176:179], v[44:47]
	v_mfma_f32_16x16x32_bf16 v[36:39], v[160:163], v[184:187], v[36:39]
	v_mfma_f32_16x16x32_bf16 v[32:35], v[168:171], v[184:187], v[32:35]
	v_mfma_f32_16x16x32_bf16 v[20:23], v[160:163], v[192:195], v[20:23]
	v_mfma_f32_16x16x32_bf16 v[12:15], v[168:171], v[192:195], v[12:15]
	v_mfma_f32_16x16x32_bf16 v[4:7], v[160:163], v[200:203], v[4:7]
	v_mfma_f32_16x16x32_bf16 v[0:3], v[168:171], v[200:203], v[0:3]
	v_mfma_f32_16x16x32_bf16 v[52:55], v[164:167], v[180:183], v[52:55]
	v_mfma_f32_16x16x32_bf16 v[44:47], v[172:175], v[180:183], v[44:47]
	v_mfma_f32_16x16x32_bf16 v[36:39], v[164:167], v[188:191], v[36:39]
	v_mfma_f32_16x16x32_bf16 v[32:35], v[172:175], v[188:191], v[32:35]
	v_mfma_f32_16x16x32_bf16 v[20:23], v[164:167], v[196:199], v[20:23]
	v_mfma_f32_16x16x32_bf16 v[12:15], v[172:175], v[196:199], v[12:15]
	v_mfma_f32_16x16x32_bf16 v[4:7], v[164:167], v[204:207], v[4:7]
	v_mfma_f32_16x16x32_bf16 v[0:3], v[172:175], v[204:207], v[0:3]
	s_setprio 0
	s_barrier
	s_add_i32 s48, s48, 2
	s_add_u32 s18, s18, 0x10000
	s_addc_u32 s19, s19, 0
	s_add_u32 s46, s46, 0x10000
	s_addc_u32 s47, s47, 0
	s_cmp_gt_u32 s48, 61
	s_cbranch_scc0 .LBB0_716
	s_and_b64 vcc, exec, s[6:7]
	s_cbranch_vccz .LBB0_719
	s_barrier
